# v8 + B-only responsibility-split L2 prefetch issued after load segment 2: waves 0-3 touch K-step t+3, waves 4-7 K-step t+4 (next unit's tile at the unit boundary), waits 8/8/9/9
# speedup vs baseline: 1.0223x; 1.0018x over previous
.LBB0_340:
	s_and_b32 s99, s54, 7
	s_lshl_b32 s99, s99, 5
	v_and_b32_e32 v244, 7, v0
	v_lshrrev_b32_e32 v245, 6, v0
	v_lshl_add_u32 v244, v245, 3, v244
	v_and_b32_e32 v245, 31, v244
	v_add_u32_e32 v245, s99, v245
	v_lshrrev_b32_e32 v246, 5, v244
	v_lshlrev_b32_e32 v245, 13, v245
	v_xor_b32_e32 v246, 1, v246
	v_lshl_add_u32 v250, v246, 7, v245
	v_mov_b32_e32 v251, 0
	v_add_u32_e32 v252, 0x10000, v159
	s_add_u32 s12, s12, 0x100080
	s_addc_u32 s13, s13, 0
	s_add_u32 s0, s14, 0x100
	v_mov_b32_e32 v2, 0
	s_addc_u32 s1, s15, 0
	s_mov_b32 s39, -2
	v_mov_b32_e32 v3, v2
	v_mov_b32_e32 v4, v2
	v_mov_b32_e32 v5, v2
	v_mov_b32_e32 v6, v2
	v_mov_b32_e32 v7, v2
	v_mov_b32_e32 v8, v2
	v_mov_b32_e32 v9, v2
	v_mov_b32_e32 v18, v2
	v_mov_b32_e32 v19, v2
	v_mov_b32_e32 v20, v2
	v_mov_b32_e32 v21, v2
	v_mov_b32_e32 v22, v2
	v_mov_b32_e32 v23, v2
	v_mov_b32_e32 v24, v2
	v_mov_b32_e32 v25, v2
	v_mov_b32_e32 v34, v2
	v_mov_b32_e32 v35, v2
	v_mov_b32_e32 v36, v2
	v_mov_b32_e32 v37, v2
	v_mov_b32_e32 v38, v2
	v_mov_b32_e32 v39, v2
	v_mov_b32_e32 v40, v2
	v_mov_b32_e32 v41, v2
	v_mov_b32_e32 v50, v2
	v_mov_b32_e32 v51, v2
	v_mov_b32_e32 v52, v2
	v_mov_b32_e32 v53, v2
	v_mov_b32_e32 v54, v2
	v_mov_b32_e32 v55, v2
	v_mov_b32_e32 v56, v2
	v_mov_b32_e32 v57, v2
	v_mov_b32_e32 v10, v2
	v_mov_b32_e32 v11, v2
	v_mov_b32_e32 v12, v2
	v_mov_b32_e32 v13, v2
	v_mov_b32_e32 v14, v2
	v_mov_b32_e32 v15, v2
	v_mov_b32_e32 v16, v2
	v_mov_b32_e32 v17, v2
	v_mov_b32_e32 v26, v2
	v_mov_b32_e32 v27, v2
	v_mov_b32_e32 v28, v2
	v_mov_b32_e32 v29, v2
	v_mov_b32_e32 v30, v2
	v_mov_b32_e32 v31, v2
	v_mov_b32_e32 v32, v2
	v_mov_b32_e32 v33, v2
	v_mov_b32_e32 v42, v2
	v_mov_b32_e32 v43, v2
	v_mov_b32_e32 v44, v2
	v_mov_b32_e32 v45, v2
	v_mov_b32_e32 v46, v2
	v_mov_b32_e32 v47, v2
	v_mov_b32_e32 v48, v2
	v_mov_b32_e32 v49, v2
	v_mov_b32_e32 v58, v2
	v_mov_b32_e32 v59, v2
	v_mov_b32_e32 v60, v2
	v_mov_b32_e32 v61, v2
	v_mov_b32_e32 v62, v2
	v_mov_b32_e32 v63, v2
	v_mov_b32_e32 v64, v2
	v_mov_b32_e32 v65, v2
	v_mov_b32_e32 v66, v2
	v_mov_b32_e32 v67, v2
	v_mov_b32_e32 v68, v2
	v_mov_b32_e32 v69, v2
	v_mov_b32_e32 v70, v2
	v_mov_b32_e32 v71, v2
	v_mov_b32_e32 v72, v2
	v_mov_b32_e32 v73, v2
	v_mov_b32_e32 v82, v2
	v_mov_b32_e32 v83, v2
	v_mov_b32_e32 v84, v2
	v_mov_b32_e32 v85, v2
	v_mov_b32_e32 v86, v2
	v_mov_b32_e32 v87, v2
	v_mov_b32_e32 v88, v2
	v_mov_b32_e32 v89, v2
	v_mov_b32_e32 v98, v2
	v_mov_b32_e32 v99, v2
	v_mov_b32_e32 v100, v2
	v_mov_b32_e32 v101, v2
	v_mov_b32_e32 v102, v2
	v_mov_b32_e32 v103, v2
	v_mov_b32_e32 v104, v2
	v_mov_b32_e32 v105, v2
	v_mov_b32_e32 v114, v2
	v_mov_b32_e32 v115, v2
	v_mov_b32_e32 v116, v2
	v_mov_b32_e32 v117, v2
	v_mov_b32_e32 v118, v2
	v_mov_b32_e32 v119, v2
	v_mov_b32_e32 v120, v2
	v_mov_b32_e32 v121, v2
	v_mov_b32_e32 v74, v2
	v_mov_b32_e32 v75, v2
	v_mov_b32_e32 v76, v2
	v_mov_b32_e32 v77, v2
	v_mov_b32_e32 v78, v2
	v_mov_b32_e32 v79, v2
	v_mov_b32_e32 v80, v2
	v_mov_b32_e32 v81, v2
	v_mov_b32_e32 v90, v2
	v_mov_b32_e32 v91, v2
	v_mov_b32_e32 v92, v2
	v_mov_b32_e32 v93, v2
	v_mov_b32_e32 v94, v2
	v_mov_b32_e32 v95, v2
	v_mov_b32_e32 v96, v2
	v_mov_b32_e32 v97, v2
	v_mov_b32_e32 v106, v2
	v_mov_b32_e32 v107, v2
	v_mov_b32_e32 v108, v2
	v_mov_b32_e32 v109, v2
	v_mov_b32_e32 v110, v2
	v_mov_b32_e32 v111, v2
	v_mov_b32_e32 v112, v2
	v_mov_b32_e32 v113, v2
	v_mov_b32_e32 v122, v2
	v_mov_b32_e32 v123, v2
	v_mov_b32_e32 v124, v2
	v_mov_b32_e32 v125, v2
	v_mov_b32_e32 v126, v2
	v_mov_b32_e32 v127, v2
	v_mov_b32_e32 v128, v2
	v_mov_b32_e32 v129, v2
.LBB0_341:
	s_add_u32 s14, s12, 0xfff00080
	s_addc_u32 s15, s13, -1
	s_cmp_eq_u32 s39, 60
	s_cselect_b32 s17, s51, s15
	s_cselect_b32 s16, s50, s14
	s_cselect_b32 s15, s53, s1
	s_cselect_b32 s14, s52, s0
	s_add_i32 m0, s8, 0xc000
	ds_read_b128 v[152:155], v252
	ds_read_b128 v[162:165], v252 offset:1024
	global_load_lds_dwordx4 v148, s[12:13]
	s_add_i32 m0, s8, 0xe000
	ds_read_b128 v[166:169], v252 offset:2048
	ds_read_b128 v[170:173], v252 offset:3072
	global_load_lds_dwordx4 v150, s[12:13]
	ds_read_b128 v[174:177], v252 offset:16384
	ds_read_b128 v[182:185], v252 offset:17408
	ds_read_b128 v[186:189], v252 offset:18432
	ds_read_b128 v[190:193], v252 offset:19456
	ds_read_b128 v[194:197], v161
	ds_read_b128 v[198:201], v161 offset:1024
	ds_read_b128 v[202:205], v161 offset:2048
	ds_read_b128 v[206:209], v161 offset:3072
	ds_read_b128 v[210:213], v161 offset:4096
	ds_read_b128 v[214:217], v161 offset:5120
	ds_read_b128 v[218:221], v161 offset:6144
	ds_read_b128 v[222:225], v161 offset:7168
	s_waitcnt vmcnt(8)
	s_waitcnt lgkmcnt(0)
	s_barrier
	v_mfma_f32_16x16x32_bf16 v[126:129], v[152:155], v[194:197], v[126:129]
	v_mfma_f32_16x16x32_bf16 v[126:129], v[162:165], v[198:201], v[126:129]
	v_mfma_f32_16x16x32_bf16 v[122:125], v[166:169], v[194:197], v[122:125]
	v_mfma_f32_16x16x32_bf16 v[122:125], v[170:173], v[198:201], v[122:125]
	v_mfma_f32_16x16x32_bf16 v[110:113], v[152:155], v[202:205], v[110:113]
	v_mfma_f32_16x16x32_bf16 v[110:113], v[162:165], v[206:209], v[110:113]
	v_mfma_f32_16x16x32_bf16 v[106:109], v[166:169], v[202:205], v[106:109]
	v_mfma_f32_16x16x32_bf16 v[106:109], v[170:173], v[206:209], v[106:109]
	v_mfma_f32_16x16x32_bf16 v[94:97], v[152:155], v[210:213], v[94:97]
	v_mfma_f32_16x16x32_bf16 v[94:97], v[162:165], v[214:217], v[94:97]
	v_mfma_f32_16x16x32_bf16 v[90:93], v[166:169], v[210:213], v[90:93]
	v_mfma_f32_16x16x32_bf16 v[90:93], v[170:173], v[214:217], v[90:93]
	v_mfma_f32_16x16x32_bf16 v[78:81], v[152:155], v[218:221], v[78:81]
	v_mfma_f32_16x16x32_bf16 v[78:81], v[162:165], v[222:225], v[78:81]
	v_mfma_f32_16x16x32_bf16 v[74:77], v[166:169], v[218:221], v[74:77]
	v_mfma_f32_16x16x32_bf16 v[74:77], v[170:173], v[222:225], v[74:77]
	v_mfma_f32_16x16x32_bf16 v[118:121], v[174:177], v[194:197], v[118:121]
	v_mfma_f32_16x16x32_bf16 v[118:121], v[182:185], v[198:201], v[118:121]
	v_mfma_f32_16x16x32_bf16 v[114:117], v[186:189], v[194:197], v[114:117]
	v_mfma_f32_16x16x32_bf16 v[114:117], v[190:193], v[198:201], v[114:117]
	v_mfma_f32_16x16x32_bf16 v[102:105], v[174:177], v[202:205], v[102:105]
	v_mfma_f32_16x16x32_bf16 v[102:105], v[182:185], v[206:209], v[102:105]
	v_mfma_f32_16x16x32_bf16 v[98:101], v[186:189], v[202:205], v[98:101]
	v_mfma_f32_16x16x32_bf16 v[98:101], v[190:193], v[206:209], v[98:101]
	v_mfma_f32_16x16x32_bf16 v[86:89], v[174:177], v[210:213], v[86:89]
	v_mfma_f32_16x16x32_bf16 v[86:89], v[182:185], v[214:217], v[86:89]
	v_mfma_f32_16x16x32_bf16 v[82:85], v[186:189], v[210:213], v[82:85]
	v_mfma_f32_16x16x32_bf16 v[82:85], v[190:193], v[214:217], v[82:85]
	v_mfma_f32_16x16x32_bf16 v[70:73], v[174:177], v[218:221], v[70:73]
	v_mfma_f32_16x16x32_bf16 v[70:73], v[182:185], v[222:225], v[70:73]
	v_mfma_f32_16x16x32_bf16 v[66:69], v[186:189], v[218:221], v[66:69]
	v_mfma_f32_16x16x32_bf16 v[66:69], v[190:193], v[222:225], v[66:69]
	s_barrier
	s_add_i32 m0, s28, 0x10000
	ds_read_b128 v[194:197], v161 offset:16384
	ds_read_b128 v[198:201], v161 offset:17408
	global_load_lds_dwordx4 v144, s[14:15]
	s_add_i32 m0, s28, 0x12000
	s_add_u32 s98, s14, 0x100000
	s_addc_u32 s99, s15, 0
	ds_read_b128 v[202:205], v161 offset:18432
	global_load_lds_dwordx4 v140, s[14:15]
	s_add_i32 m0, s28, 0x14000
	ds_read_b128 v[206:209], v161 offset:19456
	ds_read_b128 v[210:213], v161 offset:20480
	global_load_lds_dwordx4 v144, s[98:99]
	s_add_i32 m0, s28, 0x16000
	ds_read_b128 v[214:217], v161 offset:21504
	ds_read_b128 v[218:221], v161 offset:22528
	global_load_lds_dwordx4 v140, s[98:99]
	s_mov_b32 m0, s8
	ds_read_b128 v[222:225], v161 offset:23552
	global_load_lds_dwordx4 v146, s[16:17]
	s_mov_b32 m0, s9
	s_nop 0
	global_load_lds_dwordx4 v142, s[16:17]
	s_waitcnt vmcnt(8)
	s_add_u32 s100, s14, 0x100
	s_addc_u32 s101, s15, 0
	s_cmp_eq_u32 s39, 58
	s_cselect_b32 s100, s52, s100
	s_cselect_b32 s101, s53, s101
	s_bitcmp1_b32 s28, 12
	s_cselect_b32 s100, s100, s14
	s_cselect_b32 s101, s101, s15
	v_lshl_add_u64 v[242:243], s[100:101], 0, v[250:251]
	s_mov_b32 m0, 0x21800
	s_mov_b64 exec, 0xff
	s_waitcnt lgkmcnt(0)
	global_load_lds_dword v[242:243], off
	s_mov_b64 exec, -1
	s_barrier
	v_mfma_f32_16x16x32_bf16 v[62:65], v[152:155], v[194:197], v[62:65]
	v_mfma_f32_16x16x32_bf16 v[62:65], v[162:165], v[198:201], v[62:65]
	v_mfma_f32_16x16x32_bf16 v[58:61], v[166:169], v[194:197], v[58:61]
	v_mfma_f32_16x16x32_bf16 v[58:61], v[170:173], v[198:201], v[58:61]
	v_mfma_f32_16x16x32_bf16 v[46:49], v[152:155], v[202:205], v[46:49]
	v_mfma_f32_16x16x32_bf16 v[46:49], v[162:165], v[206:209], v[46:49]
	v_mfma_f32_16x16x32_bf16 v[42:45], v[166:169], v[202:205], v[42:45]
	v_mfma_f32_16x16x32_bf16 v[42:45], v[170:173], v[206:209], v[42:45]
	v_mfma_f32_16x16x32_bf16 v[30:33], v[152:155], v[210:213], v[30:33]
	v_mfma_f32_16x16x32_bf16 v[30:33], v[162:165], v[214:217], v[30:33]
	v_mfma_f32_16x16x32_bf16 v[26:29], v[166:169], v[210:213], v[26:29]
	v_mfma_f32_16x16x32_bf16 v[26:29], v[170:173], v[214:217], v[26:29]
	v_mfma_f32_16x16x32_bf16 v[14:17], v[152:155], v[218:221], v[14:17]
	v_mfma_f32_16x16x32_bf16 v[14:17], v[162:165], v[222:225], v[14:17]
	v_mfma_f32_16x16x32_bf16 v[10:13], v[166:169], v[218:221], v[10:13]
	v_mfma_f32_16x16x32_bf16 v[10:13], v[170:173], v[222:225], v[10:13]
	v_mfma_f32_16x16x32_bf16 v[54:57], v[174:177], v[194:197], v[54:57]
	v_mfma_f32_16x16x32_bf16 v[54:57], v[182:185], v[198:201], v[54:57]
	v_mfma_f32_16x16x32_bf16 v[50:53], v[186:189], v[194:197], v[50:53]
	v_mfma_f32_16x16x32_bf16 v[50:53], v[190:193], v[198:201], v[50:53]
	v_mfma_f32_16x16x32_bf16 v[38:41], v[174:177], v[202:205], v[38:41]
	v_mfma_f32_16x16x32_bf16 v[38:41], v[182:185], v[206:209], v[38:41]
	v_mfma_f32_16x16x32_bf16 v[34:37], v[186:189], v[202:205], v[34:37]
	v_mfma_f32_16x16x32_bf16 v[34:37], v[190:193], v[206:209], v[34:37]
	v_mfma_f32_16x16x32_bf16 v[22:25], v[174:177], v[210:213], v[22:25]
	v_mfma_f32_16x16x32_bf16 v[22:25], v[182:185], v[214:217], v[22:25]
	v_mfma_f32_16x16x32_bf16 v[18:21], v[186:189], v[210:213], v[18:21]
	v_mfma_f32_16x16x32_bf16 v[18:21], v[190:193], v[214:217], v[18:21]
	v_mfma_f32_16x16x32_bf16 v[6:9], v[174:177], v[218:221], v[6:9]
	v_mfma_f32_16x16x32_bf16 v[6:9], v[182:185], v[222:225], v[6:9]
	v_mfma_f32_16x16x32_bf16 v[2:5], v[186:189], v[218:221], v[2:5]
	v_mfma_f32_16x16x32_bf16 v[2:5], v[190:193], v[222:225], v[2:5]
	s_barrier
	s_add_u32 s100, s16, 0x100000
	s_addc_u32 s101, s17, 0
	s_mov_b32 m0, s29
	ds_read_b128 v[152:155], v252 offset:32768
	ds_read_b128 v[162:165], v252 offset:33792
	global_load_lds_dwordx4 v146, s[100:101]
	s_mov_b32 m0, s36
	ds_read_b128 v[166:169], v252 offset:34816
	ds_read_b128 v[170:173], v252 offset:35840
	global_load_lds_dwordx4 v142, s[100:101]
	ds_read_b128 v[174:177], v252 offset:49152
	ds_read_b128 v[182:185], v252 offset:50176
	ds_read_b128 v[186:189], v252 offset:51200
	ds_read_b128 v[190:193], v252 offset:52224
	ds_read_b128 v[194:197], v161 offset:32768
	ds_read_b128 v[198:201], v161 offset:33792
	ds_read_b128 v[202:205], v161 offset:34816
	ds_read_b128 v[206:209], v161 offset:35840
	ds_read_b128 v[210:213], v161 offset:36864
	ds_read_b128 v[214:217], v161 offset:37888
	ds_read_b128 v[218:221], v161 offset:38912
	ds_read_b128 v[222:225], v161 offset:39936
	s_waitcnt vmcnt(9)
	s_waitcnt lgkmcnt(0)
	s_barrier
	v_mfma_f32_16x16x32_bf16 v[126:129], v[152:155], v[194:197], v[126:129]
	v_mfma_f32_16x16x32_bf16 v[126:129], v[162:165], v[198:201], v[126:129]
	v_mfma_f32_16x16x32_bf16 v[122:125], v[166:169], v[194:197], v[122:125]
	v_mfma_f32_16x16x32_bf16 v[122:125], v[170:173], v[198:201], v[122:125]
	v_mfma_f32_16x16x32_bf16 v[110:113], v[152:155], v[202:205], v[110:113]
	v_mfma_f32_16x16x32_bf16 v[110:113], v[162:165], v[206:209], v[110:113]
	v_mfma_f32_16x16x32_bf16 v[106:109], v[166:169], v[202:205], v[106:109]
	v_mfma_f32_16x16x32_bf16 v[106:109], v[170:173], v[206:209], v[106:109]
	v_mfma_f32_16x16x32_bf16 v[94:97], v[152:155], v[210:213], v[94:97]
	v_mfma_f32_16x16x32_bf16 v[94:97], v[162:165], v[214:217], v[94:97]
	v_mfma_f32_16x16x32_bf16 v[90:93], v[166:169], v[210:213], v[90:93]
	v_mfma_f32_16x16x32_bf16 v[90:93], v[170:173], v[214:217], v[90:93]
	v_mfma_f32_16x16x32_bf16 v[78:81], v[152:155], v[218:221], v[78:81]
	v_mfma_f32_16x16x32_bf16 v[78:81], v[162:165], v[222:225], v[78:81]
	v_mfma_f32_16x16x32_bf16 v[74:77], v[166:169], v[218:221], v[74:77]
	v_mfma_f32_16x16x32_bf16 v[74:77], v[170:173], v[222:225], v[74:77]
	v_mfma_f32_16x16x32_bf16 v[118:121], v[174:177], v[194:197], v[118:121]
	v_mfma_f32_16x16x32_bf16 v[118:121], v[182:185], v[198:201], v[118:121]
	v_mfma_f32_16x16x32_bf16 v[114:117], v[186:189], v[194:197], v[114:117]
	v_mfma_f32_16x16x32_bf16 v[114:117], v[190:193], v[198:201], v[114:117]
	v_mfma_f32_16x16x32_bf16 v[102:105], v[174:177], v[202:205], v[102:105]
	v_mfma_f32_16x16x32_bf16 v[102:105], v[182:185], v[206:209], v[102:105]
	v_mfma_f32_16x16x32_bf16 v[98:101], v[186:189], v[202:205], v[98:101]
	v_mfma_f32_16x16x32_bf16 v[98:101], v[190:193], v[206:209], v[98:101]
	v_mfma_f32_16x16x32_bf16 v[86:89], v[174:177], v[210:213], v[86:89]
	v_mfma_f32_16x16x32_bf16 v[86:89], v[182:185], v[214:217], v[86:89]
	v_mfma_f32_16x16x32_bf16 v[82:85], v[186:189], v[210:213], v[82:85]
	v_mfma_f32_16x16x32_bf16 v[82:85], v[190:193], v[214:217], v[82:85]
	v_mfma_f32_16x16x32_bf16 v[70:73], v[174:177], v[218:221], v[70:73]
	v_mfma_f32_16x16x32_bf16 v[70:73], v[182:185], v[222:225], v[70:73]
	v_mfma_f32_16x16x32_bf16 v[66:69], v[186:189], v[218:221], v[66:69]
	v_mfma_f32_16x16x32_bf16 v[66:69], v[190:193], v[222:225], v[66:69]
	s_barrier
	s_add_u32 s14, s14, 0x80
	s_addc_u32 s15, s15, 0
	s_add_i32 m0, s28, 0x18000
	ds_read_b128 v[194:197], v161 offset:49152
	ds_read_b128 v[198:201], v161 offset:50176
	global_load_lds_dwordx4 v144, s[14:15]
	s_add_i32 m0, s28, 0x1a000
	s_add_u32 s98, s98, 0x80
	s_addc_u32 s99, s99, 0
	ds_read_b128 v[202:205], v161 offset:51200
	global_load_lds_dwordx4 v140, s[14:15]
	s_add_i32 m0, s28, 0x1c000
	ds_read_b128 v[206:209], v161 offset:52224
	ds_read_b128 v[210:213], v161 offset:53248
	global_load_lds_dwordx4 v144, s[98:99]
	s_add_i32 m0, s28, 0x1e000
	s_add_u32 s16, s16, 0x80
	s_addc_u32 s17, s17, 0
	ds_read_b128 v[214:217], v161 offset:54272
	ds_read_b128 v[218:221], v161 offset:55296
	global_load_lds_dwordx4 v140, s[98:99]
	s_mov_b32 m0, s45
	ds_read_b128 v[222:225], v161 offset:56320
	global_load_lds_dwordx4 v146, s[16:17]
	s_mov_b32 m0, s46
	s_nop 0
	global_load_lds_dwordx4 v142, s[16:17]
	s_waitcnt vmcnt(9)
	s_waitcnt lgkmcnt(0)
	s_barrier
	v_mfma_f32_16x16x32_bf16 v[62:65], v[152:155], v[194:197], v[62:65]
	v_mfma_f32_16x16x32_bf16 v[62:65], v[162:165], v[198:201], v[62:65]
	v_mfma_f32_16x16x32_bf16 v[58:61], v[166:169], v[194:197], v[58:61]
	v_mfma_f32_16x16x32_bf16 v[58:61], v[170:173], v[198:201], v[58:61]
	v_mfma_f32_16x16x32_bf16 v[46:49], v[152:155], v[202:205], v[46:49]
	v_mfma_f32_16x16x32_bf16 v[46:49], v[162:165], v[206:209], v[46:49]
	v_mfma_f32_16x16x32_bf16 v[42:45], v[166:169], v[202:205], v[42:45]
	v_mfma_f32_16x16x32_bf16 v[42:45], v[170:173], v[206:209], v[42:45]
	v_mfma_f32_16x16x32_bf16 v[30:33], v[152:155], v[210:213], v[30:33]
	v_mfma_f32_16x16x32_bf16 v[30:33], v[162:165], v[214:217], v[30:33]
	v_mfma_f32_16x16x32_bf16 v[26:29], v[166:169], v[210:213], v[26:29]
	v_mfma_f32_16x16x32_bf16 v[26:29], v[170:173], v[214:217], v[26:29]
	v_mfma_f32_16x16x32_bf16 v[14:17], v[152:155], v[218:221], v[14:17]
	v_mfma_f32_16x16x32_bf16 v[14:17], v[162:165], v[222:225], v[14:17]
	v_mfma_f32_16x16x32_bf16 v[10:13], v[166:169], v[218:221], v[10:13]
	v_mfma_f32_16x16x32_bf16 v[10:13], v[170:173], v[222:225], v[10:13]
	v_mfma_f32_16x16x32_bf16 v[54:57], v[174:177], v[194:197], v[54:57]
	v_mfma_f32_16x16x32_bf16 v[54:57], v[182:185], v[198:201], v[54:57]
	v_mfma_f32_16x16x32_bf16 v[50:53], v[186:189], v[194:197], v[50:53]
	v_mfma_f32_16x16x32_bf16 v[50:53], v[190:193], v[198:201], v[50:53]
	v_mfma_f32_16x16x32_bf16 v[38:41], v[174:177], v[202:205], v[38:41]
	v_mfma_f32_16x16x32_bf16 v[38:41], v[182:185], v[206:209], v[38:41]
	v_mfma_f32_16x16x32_bf16 v[34:37], v[186:189], v[202:205], v[34:37]
	v_mfma_f32_16x16x32_bf16 v[34:37], v[190:193], v[206:209], v[34:37]
	v_mfma_f32_16x16x32_bf16 v[22:25], v[174:177], v[210:213], v[22:25]
	v_mfma_f32_16x16x32_bf16 v[22:25], v[182:185], v[214:217], v[22:25]
	v_mfma_f32_16x16x32_bf16 v[18:21], v[186:189], v[210:213], v[18:21]
	v_mfma_f32_16x16x32_bf16 v[18:21], v[190:193], v[214:217], v[18:21]
	v_mfma_f32_16x16x32_bf16 v[6:9], v[174:177], v[218:221], v[6:9]
	v_mfma_f32_16x16x32_bf16 v[6:9], v[182:185], v[222:225], v[6:9]
	v_mfma_f32_16x16x32_bf16 v[2:5], v[186:189], v[218:221], v[2:5]
	v_mfma_f32_16x16x32_bf16 v[2:5], v[190:193], v[222:225], v[2:5]
	s_barrier
	s_add_i32 s39, s39, 2
	s_add_u32 s12, s12, 0x100
	s_addc_u32 s13, s13, 0
	s_add_u32 s0, s0, 0x100
	s_addc_u32 s1, s1, 0
	s_cmp_gt_u32 s39, 61
	s_cbranch_scc0 .LBB0_341
	s_and_b64 vcc, exec, s[34:35]
	s_cbranch_vccz .LBB0_344
	s_barrier

.LBB0_571:
	s_and_b32 s99, s46, 7
	s_lshl_b32 s99, s99, 5
	v_and_b32_e32 v244, 7, v0
	v_lshrrev_b32_e32 v245, 6, v0
	v_lshl_add_u32 v244, v245, 3, v244
	v_and_b32_e32 v245, 31, v244
	v_add_u32_e32 v245, s99, v245
	v_lshrrev_b32_e32 v246, 5, v244
	v_lshlrev_b32_e32 v245, 13, v245
	v_xor_b32_e32 v246, 1, v246
	v_lshl_add_u32 v250, v246, 7, v245
	v_mov_b32_e32 v251, 0
	v_add_u32_e32 v252, 0x10000, v159
	s_add_u32 s12, s12, 0x100080
	s_addc_u32 s13, s13, 0
	s_add_u32 s0, s14, 0x100
	v_mov_b32_e32 v2, 0
	s_addc_u32 s1, s15, 0
	s_mov_b32 s35, -2
	v_mov_b32_e32 v3, v2
	v_mov_b32_e32 v4, v2
	v_mov_b32_e32 v5, v2
	v_mov_b32_e32 v6, v2
	v_mov_b32_e32 v7, v2
	v_mov_b32_e32 v8, v2
	v_mov_b32_e32 v9, v2
	v_mov_b32_e32 v18, v2
	v_mov_b32_e32 v19, v2
	v_mov_b32_e32 v20, v2
	v_mov_b32_e32 v21, v2
	v_mov_b32_e32 v22, v2
	v_mov_b32_e32 v23, v2
	v_mov_b32_e32 v24, v2
	v_mov_b32_e32 v25, v2
	v_mov_b32_e32 v34, v2
	v_mov_b32_e32 v35, v2
	v_mov_b32_e32 v36, v2
	v_mov_b32_e32 v37, v2
	v_mov_b32_e32 v38, v2
	v_mov_b32_e32 v39, v2
	v_mov_b32_e32 v40, v2
	v_mov_b32_e32 v41, v2
	v_mov_b32_e32 v50, v2
	v_mov_b32_e32 v51, v2
	v_mov_b32_e32 v52, v2
	v_mov_b32_e32 v53, v2
	v_mov_b32_e32 v54, v2
	v_mov_b32_e32 v55, v2
	v_mov_b32_e32 v56, v2
	v_mov_b32_e32 v57, v2
	v_mov_b32_e32 v10, v2
	v_mov_b32_e32 v11, v2
	v_mov_b32_e32 v12, v2
	v_mov_b32_e32 v13, v2
	v_mov_b32_e32 v14, v2
	v_mov_b32_e32 v15, v2
	v_mov_b32_e32 v16, v2
	v_mov_b32_e32 v17, v2
	v_mov_b32_e32 v26, v2
	v_mov_b32_e32 v27, v2
	v_mov_b32_e32 v28, v2
	v_mov_b32_e32 v29, v2
	v_mov_b32_e32 v30, v2
	v_mov_b32_e32 v31, v2
	v_mov_b32_e32 v32, v2
	v_mov_b32_e32 v33, v2
	v_mov_b32_e32 v42, v2
	v_mov_b32_e32 v43, v2
	v_mov_b32_e32 v44, v2
	v_mov_b32_e32 v45, v2
	v_mov_b32_e32 v46, v2
	v_mov_b32_e32 v47, v2
	v_mov_b32_e32 v48, v2
	v_mov_b32_e32 v49, v2
	v_mov_b32_e32 v58, v2
	v_mov_b32_e32 v59, v2
	v_mov_b32_e32 v60, v2
	v_mov_b32_e32 v61, v2
	v_mov_b32_e32 v62, v2
	v_mov_b32_e32 v63, v2
	v_mov_b32_e32 v64, v2
	v_mov_b32_e32 v65, v2
	v_mov_b32_e32 v66, v2
	v_mov_b32_e32 v67, v2
	v_mov_b32_e32 v68, v2
	v_mov_b32_e32 v69, v2
	v_mov_b32_e32 v70, v2
	v_mov_b32_e32 v71, v2
	v_mov_b32_e32 v72, v2
	v_mov_b32_e32 v73, v2
	v_mov_b32_e32 v82, v2
	v_mov_b32_e32 v83, v2
	v_mov_b32_e32 v84, v2
	v_mov_b32_e32 v85, v2
	v_mov_b32_e32 v86, v2
	v_mov_b32_e32 v87, v2
	v_mov_b32_e32 v88, v2
	v_mov_b32_e32 v89, v2
	v_mov_b32_e32 v98, v2
	v_mov_b32_e32 v99, v2
	v_mov_b32_e32 v100, v2
	v_mov_b32_e32 v101, v2
	v_mov_b32_e32 v102, v2
	v_mov_b32_e32 v103, v2
	v_mov_b32_e32 v104, v2
	v_mov_b32_e32 v105, v2
	v_mov_b32_e32 v114, v2
	v_mov_b32_e32 v115, v2
	v_mov_b32_e32 v116, v2
	v_mov_b32_e32 v117, v2
	v_mov_b32_e32 v118, v2
	v_mov_b32_e32 v119, v2
	v_mov_b32_e32 v120, v2
	v_mov_b32_e32 v121, v2
	v_mov_b32_e32 v74, v2
	v_mov_b32_e32 v75, v2
	v_mov_b32_e32 v76, v2
	v_mov_b32_e32 v77, v2
	v_mov_b32_e32 v78, v2
	v_mov_b32_e32 v79, v2
	v_mov_b32_e32 v80, v2
	v_mov_b32_e32 v81, v2
	v_mov_b32_e32 v90, v2
	v_mov_b32_e32 v91, v2
	v_mov_b32_e32 v92, v2
	v_mov_b32_e32 v93, v2
	v_mov_b32_e32 v94, v2
	v_mov_b32_e32 v95, v2
	v_mov_b32_e32 v96, v2
	v_mov_b32_e32 v97, v2
	v_mov_b32_e32 v106, v2
	v_mov_b32_e32 v107, v2
	v_mov_b32_e32 v108, v2
	v_mov_b32_e32 v109, v2
	v_mov_b32_e32 v110, v2
	v_mov_b32_e32 v111, v2
	v_mov_b32_e32 v112, v2
	v_mov_b32_e32 v113, v2
	v_mov_b32_e32 v122, v2
	v_mov_b32_e32 v123, v2
	v_mov_b32_e32 v124, v2
	v_mov_b32_e32 v125, v2
	v_mov_b32_e32 v126, v2
	v_mov_b32_e32 v127, v2
	v_mov_b32_e32 v128, v2
	v_mov_b32_e32 v129, v2
.LBB0_572:
	s_add_u32 s14, s12, 0xfff00080
	s_addc_u32 s15, s13, -1
	s_cmp_eq_u32 s35, 60
	s_cselect_b32 s17, s51, s15
	s_cselect_b32 s16, s50, s14
	s_cselect_b32 s15, s53, s1
	s_cselect_b32 s14, s52, s0
	s_add_i32 m0, s8, 0xc000
	ds_read_b128 v[152:155], v252
	ds_read_b128 v[162:165], v252 offset:1024
	global_load_lds_dwordx4 v148, s[12:13]
	s_add_i32 m0, s8, 0xe000
	ds_read_b128 v[166:169], v252 offset:2048
	ds_read_b128 v[170:173], v252 offset:3072
	global_load_lds_dwordx4 v150, s[12:13]
	ds_read_b128 v[174:177], v252 offset:16384
	ds_read_b128 v[182:185], v252 offset:17408
	ds_read_b128 v[186:189], v252 offset:18432
	ds_read_b128 v[190:193], v252 offset:19456
	ds_read_b128 v[194:197], v161
	ds_read_b128 v[198:201], v161 offset:1024
	ds_read_b128 v[202:205], v161 offset:2048
	ds_read_b128 v[206:209], v161 offset:3072
	ds_read_b128 v[210:213], v161 offset:4096
	ds_read_b128 v[214:217], v161 offset:5120
	ds_read_b128 v[218:221], v161 offset:6144
	ds_read_b128 v[222:225], v161 offset:7168
	s_waitcnt vmcnt(8)
	s_waitcnt lgkmcnt(0)
	s_barrier
	v_mfma_f32_16x16x32_bf16 v[126:129], v[152:155], v[194:197], v[126:129]
	v_mfma_f32_16x16x32_bf16 v[126:129], v[162:165], v[198:201], v[126:129]
	v_mfma_f32_16x16x32_bf16 v[122:125], v[166:169], v[194:197], v[122:125]
	v_mfma_f32_16x16x32_bf16 v[122:125], v[170:173], v[198:201], v[122:125]
	v_mfma_f32_16x16x32_bf16 v[110:113], v[152:155], v[202:205], v[110:113]
	v_mfma_f32_16x16x32_bf16 v[110:113], v[162:165], v[206:209], v[110:113]
	v_mfma_f32_16x16x32_bf16 v[106:109], v[166:169], v[202:205], v[106:109]
	v_mfma_f32_16x16x32_bf16 v[106:109], v[170:173], v[206:209], v[106:109]
	v_mfma_f32_16x16x32_bf16 v[94:97], v[152:155], v[210:213], v[94:97]
	v_mfma_f32_16x16x32_bf16 v[94:97], v[162:165], v[214:217], v[94:97]
	v_mfma_f32_16x16x32_bf16 v[90:93], v[166:169], v[210:213], v[90:93]
	v_mfma_f32_16x16x32_bf16 v[90:93], v[170:173], v[214:217], v[90:93]
	v_mfma_f32_16x16x32_bf16 v[78:81], v[152:155], v[218:221], v[78:81]
	v_mfma_f32_16x16x32_bf16 v[78:81], v[162:165], v[222:225], v[78:81]
	v_mfma_f32_16x16x32_bf16 v[74:77], v[166:169], v[218:221], v[74:77]
	v_mfma_f32_16x16x32_bf16 v[74:77], v[170:173], v[222:225], v[74:77]
	v_mfma_f32_16x16x32_bf16 v[118:121], v[174:177], v[194:197], v[118:121]
	v_mfma_f32_16x16x32_bf16 v[118:121], v[182:185], v[198:201], v[118:121]
	v_mfma_f32_16x16x32_bf16 v[114:117], v[186:189], v[194:197], v[114:117]
	v_mfma_f32_16x16x32_bf16 v[114:117], v[190:193], v[198:201], v[114:117]
	v_mfma_f32_16x16x32_bf16 v[102:105], v[174:177], v[202:205], v[102:105]
	v_mfma_f32_16x16x32_bf16 v[102:105], v[182:185], v[206:209], v[102:105]
	v_mfma_f32_16x16x32_bf16 v[98:101], v[186:189], v[202:205], v[98:101]
	v_mfma_f32_16x16x32_bf16 v[98:101], v[190:193], v[206:209], v[98:101]
	v_mfma_f32_16x16x32_bf16 v[86:89], v[174:177], v[210:213], v[86:89]
	v_mfma_f32_16x16x32_bf16 v[86:89], v[182:185], v[214:217], v[86:89]
	v_mfma_f32_16x16x32_bf16 v[82:85], v[186:189], v[210:213], v[82:85]
	v_mfma_f32_16x16x32_bf16 v[82:85], v[190:193], v[214:217], v[82:85]
	v_mfma_f32_16x16x32_bf16 v[70:73], v[174:177], v[218:221], v[70:73]
	v_mfma_f32_16x16x32_bf16 v[70:73], v[182:185], v[222:225], v[70:73]
	v_mfma_f32_16x16x32_bf16 v[66:69], v[186:189], v[218:221], v[66:69]
	v_mfma_f32_16x16x32_bf16 v[66:69], v[190:193], v[222:225], v[66:69]
	s_barrier
	s_add_i32 m0, s28, 0x10000
	ds_read_b128 v[194:197], v161 offset:16384
	ds_read_b128 v[198:201], v161 offset:17408
	global_load_lds_dwordx4 v144, s[14:15]
	s_add_i32 m0, s28, 0x12000
	s_add_u32 s98, s14, 0x100000
	s_addc_u32 s99, s15, 0
	ds_read_b128 v[202:205], v161 offset:18432
	global_load_lds_dwordx4 v140, s[14:15]
	s_add_i32 m0, s28, 0x14000
	ds_read_b128 v[206:209], v161 offset:19456
	ds_read_b128 v[210:213], v161 offset:20480
	global_load_lds_dwordx4 v144, s[98:99]
	s_add_i32 m0, s28, 0x16000
	ds_read_b128 v[214:217], v161 offset:21504
	ds_read_b128 v[218:221], v161 offset:22528
	global_load_lds_dwordx4 v140, s[98:99]
	s_mov_b32 m0, s8
	ds_read_b128 v[222:225], v161 offset:23552
	global_load_lds_dwordx4 v146, s[16:17]
	s_mov_b32 m0, s9
	s_nop 0
	global_load_lds_dwordx4 v142, s[16:17]
	s_waitcnt vmcnt(8)
	s_add_u32 s100, s14, 0x100
	s_addc_u32 s101, s15, 0
	s_cmp_eq_u32 s35, 58
	s_cselect_b32 s100, s52, s100
	s_cselect_b32 s101, s53, s101
	s_bitcmp1_b32 s28, 12
	s_cselect_b32 s100, s100, s14
	s_cselect_b32 s101, s101, s15
	v_lshl_add_u64 v[242:243], s[100:101], 0, v[250:251]
	s_mov_b32 m0, 0x21800
	s_mov_b64 exec, 0xff
	s_waitcnt lgkmcnt(0)
	global_load_lds_dword v[242:243], off
	s_mov_b64 exec, -1
	s_barrier
	v_mfma_f32_16x16x32_bf16 v[62:65], v[152:155], v[194:197], v[62:65]
	v_mfma_f32_16x16x32_bf16 v[62:65], v[162:165], v[198:201], v[62:65]
	v_mfma_f32_16x16x32_bf16 v[58:61], v[166:169], v[194:197], v[58:61]
	v_mfma_f32_16x16x32_bf16 v[58:61], v[170:173], v[198:201], v[58:61]
	v_mfma_f32_16x16x32_bf16 v[46:49], v[152:155], v[202:205], v[46:49]
	v_mfma_f32_16x16x32_bf16 v[46:49], v[162:165], v[206:209], v[46:49]
	v_mfma_f32_16x16x32_bf16 v[42:45], v[166:169], v[202:205], v[42:45]
	v_mfma_f32_16x16x32_bf16 v[42:45], v[170:173], v[206:209], v[42:45]
	v_mfma_f32_16x16x32_bf16 v[30:33], v[152:155], v[210:213], v[30:33]
	v_mfma_f32_16x16x32_bf16 v[30:33], v[162:165], v[214:217], v[30:33]
	v_mfma_f32_16x16x32_bf16 v[26:29], v[166:169], v[210:213], v[26:29]
	v_mfma_f32_16x16x32_bf16 v[26:29], v[170:173], v[214:217], v[26:29]
	v_mfma_f32_16x16x32_bf16 v[14:17], v[152:155], v[218:221], v[14:17]
	v_mfma_f32_16x16x32_bf16 v[14:17], v[162:165], v[222:225], v[14:17]
	v_mfma_f32_16x16x32_bf16 v[10:13], v[166:169], v[218:221], v[10:13]
	v_mfma_f32_16x16x32_bf16 v[10:13], v[170:173], v[222:225], v[10:13]
	v_mfma_f32_16x16x32_bf16 v[54:57], v[174:177], v[194:197], v[54:57]
	v_mfma_f32_16x16x32_bf16 v[54:57], v[182:185], v[198:201], v[54:57]
	v_mfma_f32_16x16x32_bf16 v[50:53], v[186:189], v[194:197], v[50:53]
	v_mfma_f32_16x16x32_bf16 v[50:53], v[190:193], v[198:201], v[50:53]
	v_mfma_f32_16x16x32_bf16 v[38:41], v[174:177], v[202:205], v[38:41]
	v_mfma_f32_16x16x32_bf16 v[38:41], v[182:185], v[206:209], v[38:41]
	v_mfma_f32_16x16x32_bf16 v[34:37], v[186:189], v[202:205], v[34:37]
	v_mfma_f32_16x16x32_bf16 v[34:37], v[190:193], v[206:209], v[34:37]
	v_mfma_f32_16x16x32_bf16 v[22:25], v[174:177], v[210:213], v[22:25]
	v_mfma_f32_16x16x32_bf16 v[22:25], v[182:185], v[214:217], v[22:25]
	v_mfma_f32_16x16x32_bf16 v[18:21], v[186:189], v[210:213], v[18:21]
	v_mfma_f32_16x16x32_bf16 v[18:21], v[190:193], v[214:217], v[18:21]
	v_mfma_f32_16x16x32_bf16 v[6:9], v[174:177], v[218:221], v[6:9]
	v_mfma_f32_16x16x32_bf16 v[6:9], v[182:185], v[222:225], v[6:9]
	v_mfma_f32_16x16x32_bf16 v[2:5], v[186:189], v[218:221], v[2:5]
	v_mfma_f32_16x16x32_bf16 v[2:5], v[190:193], v[222:225], v[2:5]
	s_barrier
	s_add_u32 s100, s16, 0x100000
	s_addc_u32 s101, s17, 0
	s_mov_b32 m0, s29
	ds_read_b128 v[152:155], v252 offset:32768
	ds_read_b128 v[162:165], v252 offset:33792
	global_load_lds_dwordx4 v146, s[100:101]
	s_mov_b32 m0, s36
	ds_read_b128 v[166:169], v252 offset:34816
	ds_read_b128 v[170:173], v252 offset:35840
	global_load_lds_dwordx4 v142, s[100:101]
	ds_read_b128 v[174:177], v252 offset:49152
	ds_read_b128 v[182:185], v252 offset:50176
	ds_read_b128 v[186:189], v252 offset:51200
	ds_read_b128 v[190:193], v252 offset:52224
	ds_read_b128 v[194:197], v161 offset:32768
	ds_read_b128 v[198:201], v161 offset:33792
	ds_read_b128 v[202:205], v161 offset:34816
	ds_read_b128 v[206:209], v161 offset:35840
	ds_read_b128 v[210:213], v161 offset:36864
	ds_read_b128 v[214:217], v161 offset:37888
	ds_read_b128 v[218:221], v161 offset:38912
	ds_read_b128 v[222:225], v161 offset:39936
	s_waitcnt vmcnt(9)
	s_waitcnt lgkmcnt(0)
	s_barrier
	v_mfma_f32_16x16x32_bf16 v[126:129], v[152:155], v[194:197], v[126:129]
	v_mfma_f32_16x16x32_bf16 v[126:129], v[162:165], v[198:201], v[126:129]
	v_mfma_f32_16x16x32_bf16 v[122:125], v[166:169], v[194:197], v[122:125]
	v_mfma_f32_16x16x32_bf16 v[122:125], v[170:173], v[198:201], v[122:125]
	v_mfma_f32_16x16x32_bf16 v[110:113], v[152:155], v[202:205], v[110:113]
	v_mfma_f32_16x16x32_bf16 v[110:113], v[162:165], v[206:209], v[110:113]
	v_mfma_f32_16x16x32_bf16 v[106:109], v[166:169], v[202:205], v[106:109]
	v_mfma_f32_16x16x32_bf16 v[106:109], v[170:173], v[206:209], v[106:109]
	v_mfma_f32_16x16x32_bf16 v[94:97], v[152:155], v[210:213], v[94:97]
	v_mfma_f32_16x16x32_bf16 v[94:97], v[162:165], v[214:217], v[94:97]
	v_mfma_f32_16x16x32_bf16 v[90:93], v[166:169], v[210:213], v[90:93]
	v_mfma_f32_16x16x32_bf16 v[90:93], v[170:173], v[214:217], v[90:93]
	v_mfma_f32_16x16x32_bf16 v[78:81], v[152:155], v[218:221], v[78:81]
	v_mfma_f32_16x16x32_bf16 v[78:81], v[162:165], v[222:225], v[78:81]
	v_mfma_f32_16x16x32_bf16 v[74:77], v[166:169], v[218:221], v[74:77]
	v_mfma_f32_16x16x32_bf16 v[74:77], v[170:173], v[222:225], v[74:77]
	v_mfma_f32_16x16x32_bf16 v[118:121], v[174:177], v[194:197], v[118:121]
	v_mfma_f32_16x16x32_bf16 v[118:121], v[182:185], v[198:201], v[118:121]
	v_mfma_f32_16x16x32_bf16 v[114:117], v[186:189], v[194:197], v[114:117]
	v_mfma_f32_16x16x32_bf16 v[114:117], v[190:193], v[198:201], v[114:117]
	v_mfma_f32_16x16x32_bf16 v[102:105], v[174:177], v[202:205], v[102:105]
	v_mfma_f32_16x16x32_bf16 v[102:105], v[182:185], v[206:209], v[102:105]
	v_mfma_f32_16x16x32_bf16 v[98:101], v[186:189], v[202:205], v[98:101]
	v_mfma_f32_16x16x32_bf16 v[98:101], v[190:193], v[206:209], v[98:101]
	v_mfma_f32_16x16x32_bf16 v[86:89], v[174:177], v[210:213], v[86:89]
	v_mfma_f32_16x16x32_bf16 v[86:89], v[182:185], v[214:217], v[86:89]
	v_mfma_f32_16x16x32_bf16 v[82:85], v[186:189], v[210:213], v[82:85]
	v_mfma_f32_16x16x32_bf16 v[82:85], v[190:193], v[214:217], v[82:85]
	v_mfma_f32_16x16x32_bf16 v[70:73], v[174:177], v[218:221], v[70:73]
	v_mfma_f32_16x16x32_bf16 v[70:73], v[182:185], v[222:225], v[70:73]
	v_mfma_f32_16x16x32_bf16 v[66:69], v[186:189], v[218:221], v[66:69]
	v_mfma_f32_16x16x32_bf16 v[66:69], v[190:193], v[222:225], v[66:69]
	s_barrier
	s_add_u32 s14, s14, 0x80
	s_addc_u32 s15, s15, 0
	s_add_i32 m0, s28, 0x18000
	ds_read_b128 v[194:197], v161 offset:49152
	ds_read_b128 v[198:201], v161 offset:50176
	global_load_lds_dwordx4 v144, s[14:15]
	s_add_i32 m0, s28, 0x1a000
	s_add_u32 s98, s98, 0x80
	s_addc_u32 s99, s99, 0
	ds_read_b128 v[202:205], v161 offset:51200
	global_load_lds_dwordx4 v140, s[14:15]
	s_add_i32 m0, s28, 0x1c000
	ds_read_b128 v[206:209], v161 offset:52224
	ds_read_b128 v[210:213], v161 offset:53248
	global_load_lds_dwordx4 v144, s[98:99]
	s_add_i32 m0, s28, 0x1e000
	s_add_u32 s16, s16, 0x80
	s_addc_u32 s17, s17, 0
	ds_read_b128 v[214:217], v161 offset:54272
	ds_read_b128 v[218:221], v161 offset:55296
	global_load_lds_dwordx4 v140, s[98:99]
	s_mov_b32 m0, s39
	ds_read_b128 v[222:225], v161 offset:56320
	global_load_lds_dwordx4 v146, s[16:17]
	s_mov_b32 m0, s44
	s_nop 0
	global_load_lds_dwordx4 v142, s[16:17]
	s_waitcnt vmcnt(9)
	s_waitcnt lgkmcnt(0)
	s_barrier
	v_mfma_f32_16x16x32_bf16 v[62:65], v[152:155], v[194:197], v[62:65]
	v_mfma_f32_16x16x32_bf16 v[62:65], v[162:165], v[198:201], v[62:65]
	v_mfma_f32_16x16x32_bf16 v[58:61], v[166:169], v[194:197], v[58:61]
	v_mfma_f32_16x16x32_bf16 v[58:61], v[170:173], v[198:201], v[58:61]
	v_mfma_f32_16x16x32_bf16 v[46:49], v[152:155], v[202:205], v[46:49]
	v_mfma_f32_16x16x32_bf16 v[46:49], v[162:165], v[206:209], v[46:49]
	v_mfma_f32_16x16x32_bf16 v[42:45], v[166:169], v[202:205], v[42:45]
	v_mfma_f32_16x16x32_bf16 v[42:45], v[170:173], v[206:209], v[42:45]
	v_mfma_f32_16x16x32_bf16 v[30:33], v[152:155], v[210:213], v[30:33]
	v_mfma_f32_16x16x32_bf16 v[30:33], v[162:165], v[214:217], v[30:33]
	v_mfma_f32_16x16x32_bf16 v[26:29], v[166:169], v[210:213], v[26:29]
	v_mfma_f32_16x16x32_bf16 v[26:29], v[170:173], v[214:217], v[26:29]
	v_mfma_f32_16x16x32_bf16 v[14:17], v[152:155], v[218:221], v[14:17]
	v_mfma_f32_16x16x32_bf16 v[14:17], v[162:165], v[222:225], v[14:17]
	v_mfma_f32_16x16x32_bf16 v[10:13], v[166:169], v[218:221], v[10:13]
	v_mfma_f32_16x16x32_bf16 v[10:13], v[170:173], v[222:225], v[10:13]
	v_mfma_f32_16x16x32_bf16 v[54:57], v[174:177], v[194:197], v[54:57]
	v_mfma_f32_16x16x32_bf16 v[54:57], v[182:185], v[198:201], v[54:57]
	v_mfma_f32_16x16x32_bf16 v[50:53], v[186:189], v[194:197], v[50:53]
	v_mfma_f32_16x16x32_bf16 v[50:53], v[190:193], v[198:201], v[50:53]
	v_mfma_f32_16x16x32_bf16 v[38:41], v[174:177], v[202:205], v[38:41]
	v_mfma_f32_16x16x32_bf16 v[38:41], v[182:185], v[206:209], v[38:41]
	v_mfma_f32_16x16x32_bf16 v[34:37], v[186:189], v[202:205], v[34:37]
	v_mfma_f32_16x16x32_bf16 v[34:37], v[190:193], v[206:209], v[34:37]
	v_mfma_f32_16x16x32_bf16 v[22:25], v[174:177], v[210:213], v[22:25]
	v_mfma_f32_16x16x32_bf16 v[22:25], v[182:185], v[214:217], v[22:25]
	v_mfma_f32_16x16x32_bf16 v[18:21], v[186:189], v[210:213], v[18:21]
	v_mfma_f32_16x16x32_bf16 v[18:21], v[190:193], v[214:217], v[18:21]
	v_mfma_f32_16x16x32_bf16 v[6:9], v[174:177], v[218:221], v[6:9]
	v_mfma_f32_16x16x32_bf16 v[6:9], v[182:185], v[222:225], v[6:9]
	v_mfma_f32_16x16x32_bf16 v[2:5], v[186:189], v[218:221], v[2:5]
	v_mfma_f32_16x16x32_bf16 v[2:5], v[190:193], v[222:225], v[2:5]
	s_barrier
	s_add_i32 s35, s35, 2
	s_add_u32 s12, s12, 0x100
	s_addc_u32 s13, s13, 0
	s_add_u32 s0, s0, 0x100
	s_addc_u32 s1, s1, 0
	s_cmp_gt_u32 s35, 61
	s_cbranch_scc0 .LBB0_572
	s_and_b64 vcc, exec, s[10:11]
	s_cbranch_vccz .LBB0_575
	s_barrier

.LBB0_881:
	s_and_b32 s99, s28, 7
	s_lshl_b32 s99, s99, 5
	v_and_b32_e32 v244, 7, v0
	v_lshrrev_b32_e32 v245, 6, v0
	v_lshl_add_u32 v244, v245, 3, v244
	v_and_b32_e32 v245, 31, v244
	v_add_u32_e32 v245, s99, v245
	v_lshrrev_b32_e32 v246, 5, v244
	v_lshlrev_b32_e32 v245, 13, v245
	v_xor_b32_e32 v246, 1, v246
	v_lshl_add_u32 v250, v246, 7, v245
	v_mov_b32_e32 v251, 0
	v_add_u32_e32 v252, 0x10000, v155
	s_add_u32 s10, s10, 0x100080
	s_addc_u32 s11, s11, 0
	s_add_u32 s0, s38, 0x100
	v_mov_b32_e32 v4, 0
	s_addc_u32 s1, s39, 0
	s_mov_b32 s12, -2
	v_mov_b32_e32 v5, v4
	v_mov_b32_e32 v6, v4
	v_mov_b32_e32 v7, v4
	v_mov_b32_e32 v8, v4
	v_mov_b32_e32 v9, v4
	v_mov_b32_e32 v10, v4
	v_mov_b32_e32 v11, v4
	v_mov_b32_e32 v20, v4
	v_mov_b32_e32 v21, v4
	v_mov_b32_e32 v22, v4
	v_mov_b32_e32 v23, v4
	v_mov_b32_e32 v24, v4
	v_mov_b32_e32 v25, v4
	v_mov_b32_e32 v26, v4
	v_mov_b32_e32 v27, v4
	v_mov_b32_e32 v36, v4
	v_mov_b32_e32 v37, v4
	v_mov_b32_e32 v38, v4
	v_mov_b32_e32 v39, v4
	v_mov_b32_e32 v40, v4
	v_mov_b32_e32 v41, v4
	v_mov_b32_e32 v42, v4
	v_mov_b32_e32 v43, v4
	v_mov_b32_e32 v52, v4
	v_mov_b32_e32 v53, v4
	v_mov_b32_e32 v54, v4
	v_mov_b32_e32 v55, v4
	v_mov_b32_e32 v56, v4
	v_mov_b32_e32 v57, v4
	v_mov_b32_e32 v58, v4
	v_mov_b32_e32 v59, v4
	v_mov_b32_e32 v12, v4
	v_mov_b32_e32 v13, v4
	v_mov_b32_e32 v14, v4
	v_mov_b32_e32 v15, v4
	v_mov_b32_e32 v16, v4
	v_mov_b32_e32 v17, v4
	v_mov_b32_e32 v18, v4
	v_mov_b32_e32 v19, v4
	v_mov_b32_e32 v28, v4
	v_mov_b32_e32 v29, v4
	v_mov_b32_e32 v30, v4
	v_mov_b32_e32 v31, v4
	v_mov_b32_e32 v32, v4
	v_mov_b32_e32 v33, v4
	v_mov_b32_e32 v34, v4
	v_mov_b32_e32 v35, v4
	v_mov_b32_e32 v44, v4
	v_mov_b32_e32 v45, v4
	v_mov_b32_e32 v46, v4
	v_mov_b32_e32 v47, v4
	v_mov_b32_e32 v48, v4
	v_mov_b32_e32 v49, v4
	v_mov_b32_e32 v50, v4
	v_mov_b32_e32 v51, v4
	v_mov_b32_e32 v60, v4
	v_mov_b32_e32 v61, v4
	v_mov_b32_e32 v62, v4
	v_mov_b32_e32 v63, v4
	v_mov_b32_e32 v64, v4
	v_mov_b32_e32 v65, v4
	v_mov_b32_e32 v66, v4
	v_mov_b32_e32 v67, v4
	v_mov_b32_e32 v68, v4
	v_mov_b32_e32 v69, v4
	v_mov_b32_e32 v70, v4
	v_mov_b32_e32 v71, v4
	v_mov_b32_e32 v72, v4
	v_mov_b32_e32 v73, v4
	v_mov_b32_e32 v74, v4
	v_mov_b32_e32 v75, v4
	v_mov_b32_e32 v84, v4
	v_mov_b32_e32 v85, v4
	v_mov_b32_e32 v86, v4
	v_mov_b32_e32 v87, v4
	v_mov_b32_e32 v88, v4
	v_mov_b32_e32 v89, v4
	v_mov_b32_e32 v90, v4
	v_mov_b32_e32 v91, v4
	v_mov_b32_e32 v100, v4
	v_mov_b32_e32 v101, v4
	v_mov_b32_e32 v102, v4
	v_mov_b32_e32 v103, v4
	v_mov_b32_e32 v104, v4
	v_mov_b32_e32 v105, v4
	v_mov_b32_e32 v106, v4
	v_mov_b32_e32 v107, v4
	v_mov_b32_e32 v116, v4
	v_mov_b32_e32 v117, v4
	v_mov_b32_e32 v118, v4
	v_mov_b32_e32 v119, v4
	v_mov_b32_e32 v120, v4
	v_mov_b32_e32 v121, v4
	v_mov_b32_e32 v122, v4
	v_mov_b32_e32 v123, v4
	v_mov_b32_e32 v76, v4
	v_mov_b32_e32 v77, v4
	v_mov_b32_e32 v78, v4
	v_mov_b32_e32 v79, v4
	v_mov_b32_e32 v80, v4
	v_mov_b32_e32 v81, v4
	v_mov_b32_e32 v82, v4
	v_mov_b32_e32 v83, v4
	v_mov_b32_e32 v92, v4
	v_mov_b32_e32 v93, v4
	v_mov_b32_e32 v94, v4
	v_mov_b32_e32 v95, v4
	v_mov_b32_e32 v96, v4
	v_mov_b32_e32 v97, v4
	v_mov_b32_e32 v98, v4
	v_mov_b32_e32 v99, v4
	v_mov_b32_e32 v108, v4
	v_mov_b32_e32 v109, v4
	v_mov_b32_e32 v110, v4
	v_mov_b32_e32 v111, v4
	v_mov_b32_e32 v112, v4
	v_mov_b32_e32 v113, v4
	v_mov_b32_e32 v114, v4
	v_mov_b32_e32 v115, v4
	v_mov_b32_e32 v124, v4
	v_mov_b32_e32 v125, v4
	v_mov_b32_e32 v126, v4
	v_mov_b32_e32 v127, v4
	v_mov_b32_e32 v128, v4
	v_mov_b32_e32 v129, v4
	v_mov_b32_e32 v130, v4
	v_mov_b32_e32 v131, v4
.LBB0_882:
	s_add_u32 s20, s10, 0xfff00080
	s_addc_u32 s21, s11, -1
	s_cmp_eq_u32 s12, 60
	s_cselect_b32 s43, s55, s21
	s_cselect_b32 s42, s54, s20
	s_cselect_b32 s39, s37, s1
	s_cselect_b32 s38, s36, s0
	s_add_i32 m0, s29, 0xc000
	ds_read_b128 v[146:149], v252
	ds_read_b128 v[150:153], v252 offset:1024
	global_load_lds_dwordx4 v140, s[10:11]
	s_add_i32 m0, s29, 0xe000
	ds_read_b128 v[158:161], v252 offset:2048
	ds_read_b128 v[162:165], v252 offset:3072
	global_load_lds_dwordx4 v142, s[10:11]
	ds_read_b128 v[166:169], v252 offset:16384
	ds_read_b128 v[170:173], v252 offset:17408
	ds_read_b128 v[174:177], v252 offset:18432
	ds_read_b128 v[186:189], v252 offset:19456
	ds_read_b128 v[190:193], v157
	ds_read_b128 v[194:197], v157 offset:1024
	ds_read_b128 v[198:201], v157 offset:2048
	ds_read_b128 v[202:205], v157 offset:3072
	ds_read_b128 v[206:209], v157 offset:4096
	ds_read_b128 v[210:213], v157 offset:5120
	ds_read_b128 v[214:217], v157 offset:6144
	ds_read_b128 v[218:221], v157 offset:7168
	s_waitcnt vmcnt(8)
	s_waitcnt lgkmcnt(0)
	s_barrier
	v_mfma_f32_16x16x32_bf16 v[128:131], v[146:149], v[190:193], v[128:131]
	v_mfma_f32_16x16x32_bf16 v[128:131], v[150:153], v[194:197], v[128:131]
	v_mfma_f32_16x16x32_bf16 v[124:127], v[158:161], v[190:193], v[124:127]
	v_mfma_f32_16x16x32_bf16 v[124:127], v[162:165], v[194:197], v[124:127]
	v_mfma_f32_16x16x32_bf16 v[112:115], v[146:149], v[198:201], v[112:115]
	v_mfma_f32_16x16x32_bf16 v[112:115], v[150:153], v[202:205], v[112:115]
	v_mfma_f32_16x16x32_bf16 v[108:111], v[158:161], v[198:201], v[108:111]
	v_mfma_f32_16x16x32_bf16 v[108:111], v[162:165], v[202:205], v[108:111]
	v_mfma_f32_16x16x32_bf16 v[96:99], v[146:149], v[206:209], v[96:99]
	v_mfma_f32_16x16x32_bf16 v[96:99], v[150:153], v[210:213], v[96:99]
	v_mfma_f32_16x16x32_bf16 v[92:95], v[158:161], v[206:209], v[92:95]
	v_mfma_f32_16x16x32_bf16 v[92:95], v[162:165], v[210:213], v[92:95]
	v_mfma_f32_16x16x32_bf16 v[80:83], v[146:149], v[214:217], v[80:83]
	v_mfma_f32_16x16x32_bf16 v[80:83], v[150:153], v[218:221], v[80:83]
	v_mfma_f32_16x16x32_bf16 v[76:79], v[158:161], v[214:217], v[76:79]
	v_mfma_f32_16x16x32_bf16 v[76:79], v[162:165], v[218:221], v[76:79]
	v_mfma_f32_16x16x32_bf16 v[120:123], v[166:169], v[190:193], v[120:123]
	v_mfma_f32_16x16x32_bf16 v[120:123], v[170:173], v[194:197], v[120:123]
	v_mfma_f32_16x16x32_bf16 v[116:119], v[174:177], v[190:193], v[116:119]
	v_mfma_f32_16x16x32_bf16 v[116:119], v[186:189], v[194:197], v[116:119]
	v_mfma_f32_16x16x32_bf16 v[104:107], v[166:169], v[198:201], v[104:107]
	v_mfma_f32_16x16x32_bf16 v[104:107], v[170:173], v[202:205], v[104:107]
	v_mfma_f32_16x16x32_bf16 v[100:103], v[174:177], v[198:201], v[100:103]
	v_mfma_f32_16x16x32_bf16 v[100:103], v[186:189], v[202:205], v[100:103]
	v_mfma_f32_16x16x32_bf16 v[88:91], v[166:169], v[206:209], v[88:91]
	v_mfma_f32_16x16x32_bf16 v[88:91], v[170:173], v[210:213], v[88:91]
	v_mfma_f32_16x16x32_bf16 v[84:87], v[174:177], v[206:209], v[84:87]
	v_mfma_f32_16x16x32_bf16 v[84:87], v[186:189], v[210:213], v[84:87]
	v_mfma_f32_16x16x32_bf16 v[72:75], v[166:169], v[214:217], v[72:75]
	v_mfma_f32_16x16x32_bf16 v[72:75], v[170:173], v[218:221], v[72:75]
	v_mfma_f32_16x16x32_bf16 v[68:71], v[174:177], v[214:217], v[68:71]
	v_mfma_f32_16x16x32_bf16 v[68:71], v[186:189], v[218:221], v[68:71]
	s_barrier
	s_add_i32 m0, s58, 0x10000
	ds_read_b128 v[190:193], v157 offset:16384
	ds_read_b128 v[194:197], v157 offset:17408
	global_load_lds_dwordx4 v134, s[38:39]
	s_add_i32 m0, s58, 0x12000
	s_add_u32 s98, s38, 0x100000
	s_addc_u32 s99, s39, 0
	ds_read_b128 v[198:201], v157 offset:18432
	global_load_lds_dwordx4 v138, s[38:39]
	s_add_i32 m0, s58, 0x14000
	ds_read_b128 v[202:205], v157 offset:19456
	ds_read_b128 v[206:209], v157 offset:20480
	global_load_lds_dwordx4 v134, s[98:99]
	s_add_i32 m0, s58, 0x16000
	ds_read_b128 v[210:213], v157 offset:21504
	ds_read_b128 v[214:217], v157 offset:22528
	global_load_lds_dwordx4 v138, s[98:99]
	s_mov_b32 m0, s29
	ds_read_b128 v[218:221], v157 offset:23552
	global_load_lds_dwordx4 v132, s[42:43]
	s_mov_b32 m0, s31
	s_nop 0
	global_load_lds_dwordx4 v136, s[42:43]
	s_waitcnt vmcnt(8)
	s_add_u32 s100, s38, 0x100
	s_addc_u32 s101, s39, 0
	s_cmp_eq_u32 s12, 58
	s_cselect_b32 s100, s36, s100
	s_cselect_b32 s101, s37, s101
	s_bitcmp1_b32 s58, 12
	s_cselect_b32 s100, s100, s38
	s_cselect_b32 s101, s101, s39
	v_lshl_add_u64 v[242:243], s[100:101], 0, v[250:251]
	s_mov_b32 m0, 0x21800
	s_mov_b64 exec, 0xff
	s_waitcnt lgkmcnt(0)
	global_load_lds_dword v[242:243], off
	s_mov_b64 exec, -1
	s_barrier
	v_mfma_f32_16x16x32_bf16 v[64:67], v[146:149], v[190:193], v[64:67]
	v_mfma_f32_16x16x32_bf16 v[64:67], v[150:153], v[194:197], v[64:67]
	v_mfma_f32_16x16x32_bf16 v[60:63], v[158:161], v[190:193], v[60:63]
	v_mfma_f32_16x16x32_bf16 v[60:63], v[162:165], v[194:197], v[60:63]
	v_mfma_f32_16x16x32_bf16 v[48:51], v[146:149], v[198:201], v[48:51]
	v_mfma_f32_16x16x32_bf16 v[48:51], v[150:153], v[202:205], v[48:51]
	v_mfma_f32_16x16x32_bf16 v[44:47], v[158:161], v[198:201], v[44:47]
	v_mfma_f32_16x16x32_bf16 v[44:47], v[162:165], v[202:205], v[44:47]
	v_mfma_f32_16x16x32_bf16 v[32:35], v[146:149], v[206:209], v[32:35]
	v_mfma_f32_16x16x32_bf16 v[32:35], v[150:153], v[210:213], v[32:35]
	v_mfma_f32_16x16x32_bf16 v[28:31], v[158:161], v[206:209], v[28:31]
	v_mfma_f32_16x16x32_bf16 v[28:31], v[162:165], v[210:213], v[28:31]
	v_mfma_f32_16x16x32_bf16 v[16:19], v[146:149], v[214:217], v[16:19]
	v_mfma_f32_16x16x32_bf16 v[16:19], v[150:153], v[218:221], v[16:19]
	v_mfma_f32_16x16x32_bf16 v[12:15], v[158:161], v[214:217], v[12:15]
	v_mfma_f32_16x16x32_bf16 v[12:15], v[162:165], v[218:221], v[12:15]
	v_mfma_f32_16x16x32_bf16 v[56:59], v[166:169], v[190:193], v[56:59]
	v_mfma_f32_16x16x32_bf16 v[56:59], v[170:173], v[194:197], v[56:59]
	v_mfma_f32_16x16x32_bf16 v[52:55], v[174:177], v[190:193], v[52:55]
	v_mfma_f32_16x16x32_bf16 v[52:55], v[186:189], v[194:197], v[52:55]
	v_mfma_f32_16x16x32_bf16 v[40:43], v[166:169], v[198:201], v[40:43]
	v_mfma_f32_16x16x32_bf16 v[40:43], v[170:173], v[202:205], v[40:43]
	v_mfma_f32_16x16x32_bf16 v[36:39], v[174:177], v[198:201], v[36:39]
	v_mfma_f32_16x16x32_bf16 v[36:39], v[186:189], v[202:205], v[36:39]
	v_mfma_f32_16x16x32_bf16 v[24:27], v[166:169], v[206:209], v[24:27]
	v_mfma_f32_16x16x32_bf16 v[24:27], v[170:173], v[210:213], v[24:27]
	v_mfma_f32_16x16x32_bf16 v[20:23], v[174:177], v[206:209], v[20:23]
	v_mfma_f32_16x16x32_bf16 v[20:23], v[186:189], v[210:213], v[20:23]
	v_mfma_f32_16x16x32_bf16 v[8:11], v[166:169], v[214:217], v[8:11]
	v_mfma_f32_16x16x32_bf16 v[8:11], v[170:173], v[218:221], v[8:11]
	v_mfma_f32_16x16x32_bf16 v[4:7], v[174:177], v[214:217], v[4:7]
	v_mfma_f32_16x16x32_bf16 v[4:7], v[186:189], v[218:221], v[4:7]
	s_barrier
	s_add_u32 s100, s42, 0x100000
	s_addc_u32 s101, s43, 0
	s_mov_b32 m0, s59
	ds_read_b128 v[146:149], v252 offset:32768
	ds_read_b128 v[150:153], v252 offset:33792
	global_load_lds_dwordx4 v132, s[100:101]
	s_mov_b32 m0, s94
	ds_read_b128 v[158:161], v252 offset:34816
	ds_read_b128 v[162:165], v252 offset:35840
	global_load_lds_dwordx4 v136, s[100:101]
	ds_read_b128 v[166:169], v252 offset:49152
	ds_read_b128 v[170:173], v252 offset:50176
	ds_read_b128 v[174:177], v252 offset:51200
	ds_read_b128 v[186:189], v252 offset:52224
	ds_read_b128 v[190:193], v157 offset:32768
	ds_read_b128 v[194:197], v157 offset:33792
	ds_read_b128 v[198:201], v157 offset:34816
	ds_read_b128 v[202:205], v157 offset:35840
	ds_read_b128 v[206:209], v157 offset:36864
	ds_read_b128 v[210:213], v157 offset:37888
	ds_read_b128 v[214:217], v157 offset:38912
	ds_read_b128 v[218:221], v157 offset:39936
	s_waitcnt vmcnt(9)
	s_waitcnt lgkmcnt(0)
	s_barrier
	v_mfma_f32_16x16x32_bf16 v[128:131], v[146:149], v[190:193], v[128:131]
	v_mfma_f32_16x16x32_bf16 v[128:131], v[150:153], v[194:197], v[128:131]
	v_mfma_f32_16x16x32_bf16 v[124:127], v[158:161], v[190:193], v[124:127]
	v_mfma_f32_16x16x32_bf16 v[124:127], v[162:165], v[194:197], v[124:127]
	v_mfma_f32_16x16x32_bf16 v[112:115], v[146:149], v[198:201], v[112:115]
	v_mfma_f32_16x16x32_bf16 v[112:115], v[150:153], v[202:205], v[112:115]
	v_mfma_f32_16x16x32_bf16 v[108:111], v[158:161], v[198:201], v[108:111]
	v_mfma_f32_16x16x32_bf16 v[108:111], v[162:165], v[202:205], v[108:111]
	v_mfma_f32_16x16x32_bf16 v[96:99], v[146:149], v[206:209], v[96:99]
	v_mfma_f32_16x16x32_bf16 v[96:99], v[150:153], v[210:213], v[96:99]
	v_mfma_f32_16x16x32_bf16 v[92:95], v[158:161], v[206:209], v[92:95]
	v_mfma_f32_16x16x32_bf16 v[92:95], v[162:165], v[210:213], v[92:95]
	v_mfma_f32_16x16x32_bf16 v[80:83], v[146:149], v[214:217], v[80:83]
	v_mfma_f32_16x16x32_bf16 v[80:83], v[150:153], v[218:221], v[80:83]
	v_mfma_f32_16x16x32_bf16 v[76:79], v[158:161], v[214:217], v[76:79]
	v_mfma_f32_16x16x32_bf16 v[76:79], v[162:165], v[218:221], v[76:79]
	v_mfma_f32_16x16x32_bf16 v[120:123], v[166:169], v[190:193], v[120:123]
	v_mfma_f32_16x16x32_bf16 v[120:123], v[170:173], v[194:197], v[120:123]
	v_mfma_f32_16x16x32_bf16 v[116:119], v[174:177], v[190:193], v[116:119]
	v_mfma_f32_16x16x32_bf16 v[116:119], v[186:189], v[194:197], v[116:119]
	v_mfma_f32_16x16x32_bf16 v[104:107], v[166:169], v[198:201], v[104:107]
	v_mfma_f32_16x16x32_bf16 v[104:107], v[170:173], v[202:205], v[104:107]
	v_mfma_f32_16x16x32_bf16 v[100:103], v[174:177], v[198:201], v[100:103]
	v_mfma_f32_16x16x32_bf16 v[100:103], v[186:189], v[202:205], v[100:103]
	v_mfma_f32_16x16x32_bf16 v[88:91], v[166:169], v[206:209], v[88:91]
	v_mfma_f32_16x16x32_bf16 v[88:91], v[170:173], v[210:213], v[88:91]
	v_mfma_f32_16x16x32_bf16 v[84:87], v[174:177], v[206:209], v[84:87]
	v_mfma_f32_16x16x32_bf16 v[84:87], v[186:189], v[210:213], v[84:87]
	v_mfma_f32_16x16x32_bf16 v[72:75], v[166:169], v[214:217], v[72:75]
	v_mfma_f32_16x16x32_bf16 v[72:75], v[170:173], v[218:221], v[72:75]
	v_mfma_f32_16x16x32_bf16 v[68:71], v[174:177], v[214:217], v[68:71]
	v_mfma_f32_16x16x32_bf16 v[68:71], v[186:189], v[218:221], v[68:71]
	s_barrier
	s_add_u32 s38, s38, 0x80
	s_addc_u32 s39, s39, 0
	s_add_i32 m0, s58, 0x18000
	ds_read_b128 v[190:193], v157 offset:49152
	ds_read_b128 v[194:197], v157 offset:50176
	global_load_lds_dwordx4 v134, s[38:39]
	s_add_i32 m0, s58, 0x1a000
	s_add_u32 s98, s98, 0x80
	s_addc_u32 s99, s99, 0
	ds_read_b128 v[198:201], v157 offset:51200
	global_load_lds_dwordx4 v138, s[38:39]
	s_add_i32 m0, s58, 0x1c000
	ds_read_b128 v[202:205], v157 offset:52224
	ds_read_b128 v[206:209], v157 offset:53248
	global_load_lds_dwordx4 v134, s[98:99]
	s_add_i32 m0, s58, 0x1e000
	s_add_u32 s42, s42, 0x80
	s_addc_u32 s43, s43, 0
	ds_read_b128 v[210:213], v157 offset:54272
	ds_read_b128 v[214:217], v157 offset:55296
	global_load_lds_dwordx4 v138, s[98:99]
	s_mov_b32 m0, s14
	ds_read_b128 v[218:221], v157 offset:56320
	global_load_lds_dwordx4 v132, s[42:43]
	s_mov_b32 m0, s15
	s_nop 0
	global_load_lds_dwordx4 v136, s[42:43]
	s_waitcnt vmcnt(9)
	s_waitcnt lgkmcnt(0)
	s_barrier
	v_mfma_f32_16x16x32_bf16 v[64:67], v[146:149], v[190:193], v[64:67]
	v_mfma_f32_16x16x32_bf16 v[64:67], v[150:153], v[194:197], v[64:67]
	v_mfma_f32_16x16x32_bf16 v[60:63], v[158:161], v[190:193], v[60:63]
	v_mfma_f32_16x16x32_bf16 v[60:63], v[162:165], v[194:197], v[60:63]
	v_mfma_f32_16x16x32_bf16 v[48:51], v[146:149], v[198:201], v[48:51]
	v_mfma_f32_16x16x32_bf16 v[48:51], v[150:153], v[202:205], v[48:51]
	v_mfma_f32_16x16x32_bf16 v[44:47], v[158:161], v[198:201], v[44:47]
	v_mfma_f32_16x16x32_bf16 v[44:47], v[162:165], v[202:205], v[44:47]
	v_mfma_f32_16x16x32_bf16 v[32:35], v[146:149], v[206:209], v[32:35]
	v_mfma_f32_16x16x32_bf16 v[32:35], v[150:153], v[210:213], v[32:35]
	v_mfma_f32_16x16x32_bf16 v[28:31], v[158:161], v[206:209], v[28:31]
	v_mfma_f32_16x16x32_bf16 v[28:31], v[162:165], v[210:213], v[28:31]
	v_mfma_f32_16x16x32_bf16 v[16:19], v[146:149], v[214:217], v[16:19]
	v_mfma_f32_16x16x32_bf16 v[16:19], v[150:153], v[218:221], v[16:19]
	v_mfma_f32_16x16x32_bf16 v[12:15], v[158:161], v[214:217], v[12:15]
	v_mfma_f32_16x16x32_bf16 v[12:15], v[162:165], v[218:221], v[12:15]
	v_mfma_f32_16x16x32_bf16 v[56:59], v[166:169], v[190:193], v[56:59]
	v_mfma_f32_16x16x32_bf16 v[56:59], v[170:173], v[194:197], v[56:59]
	v_mfma_f32_16x16x32_bf16 v[52:55], v[174:177], v[190:193], v[52:55]
	v_mfma_f32_16x16x32_bf16 v[52:55], v[186:189], v[194:197], v[52:55]
	v_mfma_f32_16x16x32_bf16 v[40:43], v[166:169], v[198:201], v[40:43]
	v_mfma_f32_16x16x32_bf16 v[40:43], v[170:173], v[202:205], v[40:43]
	v_mfma_f32_16x16x32_bf16 v[36:39], v[174:177], v[198:201], v[36:39]
	v_mfma_f32_16x16x32_bf16 v[36:39], v[186:189], v[202:205], v[36:39]
	v_mfma_f32_16x16x32_bf16 v[24:27], v[166:169], v[206:209], v[24:27]
	v_mfma_f32_16x16x32_bf16 v[24:27], v[170:173], v[210:213], v[24:27]
	v_mfma_f32_16x16x32_bf16 v[20:23], v[174:177], v[206:209], v[20:23]
	v_mfma_f32_16x16x32_bf16 v[20:23], v[186:189], v[210:213], v[20:23]
	v_mfma_f32_16x16x32_bf16 v[8:11], v[166:169], v[214:217], v[8:11]
	v_mfma_f32_16x16x32_bf16 v[8:11], v[170:173], v[218:221], v[8:11]
	v_mfma_f32_16x16x32_bf16 v[4:7], v[174:177], v[214:217], v[4:7]
	v_mfma_f32_16x16x32_bf16 v[4:7], v[186:189], v[218:221], v[4:7]
	s_barrier
	s_add_i32 s12, s12, 2
	s_add_u32 s10, s10, 0x100
	s_addc_u32 s11, s11, 0
	s_add_u32 s0, s0, 0x100
	s_addc_u32 s1, s1, 0
	s_cmp_gt_u32 s12, 61
	s_cbranch_scc0 .LBB0_882
	s_and_b64 vcc, exec, s[48:49]
	s_cbranch_vccz .LBB0_885
	s_barrier

.LBB0_1225:
	s_and_b32 s99, s58, 7
	s_lshl_b32 s99, s99, 5
	v_and_b32_e32 v244, 7, v0
	v_lshrrev_b32_e32 v245, 6, v0
	v_lshl_add_u32 v244, v245, 3, v244
	v_and_b32_e32 v245, 31, v244
	v_add_u32_e32 v245, s99, v245
	v_lshrrev_b32_e32 v246, 5, v244
	v_lshlrev_b32_e32 v245, 13, v245
	v_xor_b32_e32 v246, 1, v246
	v_lshl_add_u32 v250, v246, 7, v245
	v_mov_b32_e32 v251, 0
	v_add_u32_e32 v252, 0x10000, v151
	s_add_u32 s10, s10, 0x100080
	s_addc_u32 s11, s11, 0
	s_add_u32 s0, s28, 0x100
	v_mov_b32_e32 v4, 0
	s_addc_u32 s1, s29, 0
	s_mov_b32 s20, -2
	v_mov_b32_e32 v5, v4
	v_mov_b32_e32 v6, v4
	v_mov_b32_e32 v7, v4
	v_mov_b32_e32 v8, v4
	v_mov_b32_e32 v9, v4
	v_mov_b32_e32 v10, v4
	v_mov_b32_e32 v11, v4
	v_mov_b32_e32 v20, v4
	v_mov_b32_e32 v21, v4
	v_mov_b32_e32 v22, v4
	v_mov_b32_e32 v23, v4
	v_mov_b32_e32 v24, v4
	v_mov_b32_e32 v25, v4
	v_mov_b32_e32 v26, v4
	v_mov_b32_e32 v27, v4
	v_mov_b32_e32 v36, v4
	v_mov_b32_e32 v37, v4
	v_mov_b32_e32 v38, v4
	v_mov_b32_e32 v39, v4
	v_mov_b32_e32 v40, v4
	v_mov_b32_e32 v41, v4
	v_mov_b32_e32 v42, v4
	v_mov_b32_e32 v43, v4
	v_mov_b32_e32 v52, v4
	v_mov_b32_e32 v53, v4
	v_mov_b32_e32 v54, v4
	v_mov_b32_e32 v55, v4
	v_mov_b32_e32 v56, v4
	v_mov_b32_e32 v57, v4
	v_mov_b32_e32 v58, v4
	v_mov_b32_e32 v59, v4
	v_mov_b32_e32 v12, v4
	v_mov_b32_e32 v13, v4
	v_mov_b32_e32 v14, v4
	v_mov_b32_e32 v15, v4
	v_mov_b32_e32 v16, v4
	v_mov_b32_e32 v17, v4
	v_mov_b32_e32 v18, v4
	v_mov_b32_e32 v19, v4
	v_mov_b32_e32 v28, v4
	v_mov_b32_e32 v29, v4
	v_mov_b32_e32 v30, v4
	v_mov_b32_e32 v31, v4
	v_mov_b32_e32 v32, v4
	v_mov_b32_e32 v33, v4
	v_mov_b32_e32 v34, v4
	v_mov_b32_e32 v35, v4
	v_mov_b32_e32 v44, v4
	v_mov_b32_e32 v45, v4
	v_mov_b32_e32 v46, v4
	v_mov_b32_e32 v47, v4
	v_mov_b32_e32 v48, v4
	v_mov_b32_e32 v49, v4
	v_mov_b32_e32 v50, v4
	v_mov_b32_e32 v51, v4
	v_mov_b32_e32 v60, v4
	v_mov_b32_e32 v61, v4
	v_mov_b32_e32 v62, v4
	v_mov_b32_e32 v63, v4
	v_mov_b32_e32 v64, v4
	v_mov_b32_e32 v65, v4
	v_mov_b32_e32 v66, v4
	v_mov_b32_e32 v67, v4
	v_mov_b32_e32 v68, v4
	v_mov_b32_e32 v69, v4
	v_mov_b32_e32 v70, v4
	v_mov_b32_e32 v71, v4
	v_mov_b32_e32 v72, v4
	v_mov_b32_e32 v73, v4
	v_mov_b32_e32 v74, v4
	v_mov_b32_e32 v75, v4
	v_mov_b32_e32 v84, v4
	v_mov_b32_e32 v85, v4
	v_mov_b32_e32 v86, v4
	v_mov_b32_e32 v87, v4
	v_mov_b32_e32 v88, v4
	v_mov_b32_e32 v89, v4
	v_mov_b32_e32 v90, v4
	v_mov_b32_e32 v91, v4
	v_mov_b32_e32 v100, v4
	v_mov_b32_e32 v101, v4
	v_mov_b32_e32 v102, v4
	v_mov_b32_e32 v103, v4
	v_mov_b32_e32 v104, v4
	v_mov_b32_e32 v105, v4
	v_mov_b32_e32 v106, v4
	v_mov_b32_e32 v107, v4
	v_mov_b32_e32 v116, v4
	v_mov_b32_e32 v117, v4
	v_mov_b32_e32 v118, v4
	v_mov_b32_e32 v119, v4
	v_mov_b32_e32 v120, v4
	v_mov_b32_e32 v121, v4
	v_mov_b32_e32 v122, v4
	v_mov_b32_e32 v123, v4
	v_mov_b32_e32 v76, v4
	v_mov_b32_e32 v77, v4
	v_mov_b32_e32 v78, v4
	v_mov_b32_e32 v79, v4
	v_mov_b32_e32 v80, v4
	v_mov_b32_e32 v81, v4
	v_mov_b32_e32 v82, v4
	v_mov_b32_e32 v83, v4
	v_mov_b32_e32 v92, v4
	v_mov_b32_e32 v93, v4
	v_mov_b32_e32 v94, v4
	v_mov_b32_e32 v95, v4
	v_mov_b32_e32 v96, v4
	v_mov_b32_e32 v97, v4
	v_mov_b32_e32 v98, v4
	v_mov_b32_e32 v99, v4
	v_mov_b32_e32 v108, v4
	v_mov_b32_e32 v109, v4
	v_mov_b32_e32 v110, v4
	v_mov_b32_e32 v111, v4
	v_mov_b32_e32 v112, v4
	v_mov_b32_e32 v113, v4
	v_mov_b32_e32 v114, v4
	v_mov_b32_e32 v115, v4
	v_mov_b32_e32 v124, v4
	v_mov_b32_e32 v125, v4
	v_mov_b32_e32 v126, v4
	v_mov_b32_e32 v127, v4
	v_mov_b32_e32 v128, v4
	v_mov_b32_e32 v129, v4
	v_mov_b32_e32 v130, v4
	v_mov_b32_e32 v131, v4
.LBB0_1226:
	s_add_u32 s21, s10, 0xfff00080
	s_addc_u32 s22, s11, -1
	s_cmp_eq_u32 s20, 60
	s_cselect_b32 s31, s53, s22
	s_cselect_b32 s30, s52, s21
	s_cselect_b32 s29, s55, s1
	s_cselect_b32 s28, s54, s0
	s_add_i32 m0, s8, 0xc000
	ds_read_b128 v[144:147], v252
	ds_read_b128 v[154:157], v252 offset:1024
	global_load_lds_dwordx4 v140, s[10:11]
	s_add_i32 m0, s8, 0xe000
	ds_read_b128 v[158:161], v252 offset:2048
	ds_read_b128 v[162:165], v252 offset:3072
	global_load_lds_dwordx4 v142, s[10:11]
	ds_read_b128 v[166:169], v252 offset:16384
	ds_read_b128 v[170:173], v252 offset:17408
	ds_read_b128 v[174:177], v252 offset:18432
	ds_read_b128 v[186:189], v252 offset:19456
	ds_read_b128 v[190:193], v153
	ds_read_b128 v[194:197], v153 offset:1024
	ds_read_b128 v[198:201], v153 offset:2048
	ds_read_b128 v[202:205], v153 offset:3072
	ds_read_b128 v[206:209], v153 offset:4096
	ds_read_b128 v[210:213], v153 offset:5120
	ds_read_b128 v[214:217], v153 offset:6144
	ds_read_b128 v[218:221], v153 offset:7168
	s_waitcnt vmcnt(8)
	s_waitcnt lgkmcnt(0)
	s_barrier
	v_mfma_f32_16x16x32_bf16 v[128:131], v[144:147], v[190:193], v[128:131]
	v_mfma_f32_16x16x32_bf16 v[128:131], v[154:157], v[194:197], v[128:131]
	v_mfma_f32_16x16x32_bf16 v[124:127], v[158:161], v[190:193], v[124:127]
	v_mfma_f32_16x16x32_bf16 v[124:127], v[162:165], v[194:197], v[124:127]
	v_mfma_f32_16x16x32_bf16 v[112:115], v[144:147], v[198:201], v[112:115]
	v_mfma_f32_16x16x32_bf16 v[112:115], v[154:157], v[202:205], v[112:115]
	v_mfma_f32_16x16x32_bf16 v[108:111], v[158:161], v[198:201], v[108:111]
	v_mfma_f32_16x16x32_bf16 v[108:111], v[162:165], v[202:205], v[108:111]
	v_mfma_f32_16x16x32_bf16 v[96:99], v[144:147], v[206:209], v[96:99]
	v_mfma_f32_16x16x32_bf16 v[96:99], v[154:157], v[210:213], v[96:99]
	v_mfma_f32_16x16x32_bf16 v[92:95], v[158:161], v[206:209], v[92:95]
	v_mfma_f32_16x16x32_bf16 v[92:95], v[162:165], v[210:213], v[92:95]
	v_mfma_f32_16x16x32_bf16 v[80:83], v[144:147], v[214:217], v[80:83]
	v_mfma_f32_16x16x32_bf16 v[80:83], v[154:157], v[218:221], v[80:83]
	v_mfma_f32_16x16x32_bf16 v[76:79], v[158:161], v[214:217], v[76:79]
	v_mfma_f32_16x16x32_bf16 v[76:79], v[162:165], v[218:221], v[76:79]
	v_mfma_f32_16x16x32_bf16 v[120:123], v[166:169], v[190:193], v[120:123]
	v_mfma_f32_16x16x32_bf16 v[120:123], v[170:173], v[194:197], v[120:123]
	v_mfma_f32_16x16x32_bf16 v[116:119], v[174:177], v[190:193], v[116:119]
	v_mfma_f32_16x16x32_bf16 v[116:119], v[186:189], v[194:197], v[116:119]
	v_mfma_f32_16x16x32_bf16 v[104:107], v[166:169], v[198:201], v[104:107]
	v_mfma_f32_16x16x32_bf16 v[104:107], v[170:173], v[202:205], v[104:107]
	v_mfma_f32_16x16x32_bf16 v[100:103], v[174:177], v[198:201], v[100:103]
	v_mfma_f32_16x16x32_bf16 v[100:103], v[186:189], v[202:205], v[100:103]
	v_mfma_f32_16x16x32_bf16 v[88:91], v[166:169], v[206:209], v[88:91]
	v_mfma_f32_16x16x32_bf16 v[88:91], v[170:173], v[210:213], v[88:91]
	v_mfma_f32_16x16x32_bf16 v[84:87], v[174:177], v[206:209], v[84:87]
	v_mfma_f32_16x16x32_bf16 v[84:87], v[186:189], v[210:213], v[84:87]
	v_mfma_f32_16x16x32_bf16 v[72:75], v[166:169], v[214:217], v[72:75]
	v_mfma_f32_16x16x32_bf16 v[72:75], v[170:173], v[218:221], v[72:75]
	v_mfma_f32_16x16x32_bf16 v[68:71], v[174:177], v[214:217], v[68:71]
	v_mfma_f32_16x16x32_bf16 v[68:71], v[186:189], v[218:221], v[68:71]
	s_barrier
	s_add_i32 m0, s38, 0x10000
	ds_read_b128 v[190:193], v153 offset:16384
	ds_read_b128 v[194:197], v153 offset:17408
	global_load_lds_dwordx4 v136, s[28:29]
	s_add_i32 m0, s38, 0x12000
	s_add_u32 s98, s28, 0x100000
	s_addc_u32 s99, s29, 0
	ds_read_b128 v[198:201], v153 offset:18432
	global_load_lds_dwordx4 v132, s[28:29]
	s_add_i32 m0, s38, 0x14000
	ds_read_b128 v[202:205], v153 offset:19456
	ds_read_b128 v[206:209], v153 offset:20480
	global_load_lds_dwordx4 v136, s[98:99]
	s_add_i32 m0, s38, 0x16000
	ds_read_b128 v[210:213], v153 offset:21504
	ds_read_b128 v[214:217], v153 offset:22528
	global_load_lds_dwordx4 v132, s[98:99]
	s_mov_b32 m0, s8
	ds_read_b128 v[218:221], v153 offset:23552
	global_load_lds_dwordx4 v138, s[30:31]
	s_mov_b32 m0, s9
	s_nop 0
	global_load_lds_dwordx4 v134, s[30:31]
	s_waitcnt vmcnt(8)
	s_add_u32 s100, s28, 0x100
	s_addc_u32 s101, s29, 0
	s_cmp_eq_u32 s20, 58
	s_cselect_b32 s100, s54, s100
	s_cselect_b32 s101, s55, s101
	s_bitcmp1_b32 s38, 12
	s_cselect_b32 s100, s100, s28
	s_cselect_b32 s101, s101, s29
	v_lshl_add_u64 v[242:243], s[100:101], 0, v[250:251]
	s_mov_b32 m0, 0x21800
	s_mov_b64 exec, 0xff
	s_waitcnt lgkmcnt(0)
	global_load_lds_dword v[242:243], off
	s_mov_b64 exec, -1
	s_barrier
	v_mfma_f32_16x16x32_bf16 v[64:67], v[144:147], v[190:193], v[64:67]
	v_mfma_f32_16x16x32_bf16 v[64:67], v[154:157], v[194:197], v[64:67]
	v_mfma_f32_16x16x32_bf16 v[60:63], v[158:161], v[190:193], v[60:63]
	v_mfma_f32_16x16x32_bf16 v[60:63], v[162:165], v[194:197], v[60:63]
	v_mfma_f32_16x16x32_bf16 v[48:51], v[144:147], v[198:201], v[48:51]
	v_mfma_f32_16x16x32_bf16 v[48:51], v[154:157], v[202:205], v[48:51]
	v_mfma_f32_16x16x32_bf16 v[44:47], v[158:161], v[198:201], v[44:47]
	v_mfma_f32_16x16x32_bf16 v[44:47], v[162:165], v[202:205], v[44:47]
	v_mfma_f32_16x16x32_bf16 v[32:35], v[144:147], v[206:209], v[32:35]
	v_mfma_f32_16x16x32_bf16 v[32:35], v[154:157], v[210:213], v[32:35]
	v_mfma_f32_16x16x32_bf16 v[28:31], v[158:161], v[206:209], v[28:31]
	v_mfma_f32_16x16x32_bf16 v[28:31], v[162:165], v[210:213], v[28:31]
	v_mfma_f32_16x16x32_bf16 v[16:19], v[144:147], v[214:217], v[16:19]
	v_mfma_f32_16x16x32_bf16 v[16:19], v[154:157], v[218:221], v[16:19]
	v_mfma_f32_16x16x32_bf16 v[12:15], v[158:161], v[214:217], v[12:15]
	v_mfma_f32_16x16x32_bf16 v[12:15], v[162:165], v[218:221], v[12:15]
	v_mfma_f32_16x16x32_bf16 v[56:59], v[166:169], v[190:193], v[56:59]
	v_mfma_f32_16x16x32_bf16 v[56:59], v[170:173], v[194:197], v[56:59]
	v_mfma_f32_16x16x32_bf16 v[52:55], v[174:177], v[190:193], v[52:55]
	v_mfma_f32_16x16x32_bf16 v[52:55], v[186:189], v[194:197], v[52:55]
	v_mfma_f32_16x16x32_bf16 v[40:43], v[166:169], v[198:201], v[40:43]
	v_mfma_f32_16x16x32_bf16 v[40:43], v[170:173], v[202:205], v[40:43]
	v_mfma_f32_16x16x32_bf16 v[36:39], v[174:177], v[198:201], v[36:39]
	v_mfma_f32_16x16x32_bf16 v[36:39], v[186:189], v[202:205], v[36:39]
	v_mfma_f32_16x16x32_bf16 v[24:27], v[166:169], v[206:209], v[24:27]
	v_mfma_f32_16x16x32_bf16 v[24:27], v[170:173], v[210:213], v[24:27]
	v_mfma_f32_16x16x32_bf16 v[20:23], v[174:177], v[206:209], v[20:23]
	v_mfma_f32_16x16x32_bf16 v[20:23], v[186:189], v[210:213], v[20:23]
	v_mfma_f32_16x16x32_bf16 v[8:11], v[166:169], v[214:217], v[8:11]
	v_mfma_f32_16x16x32_bf16 v[8:11], v[170:173], v[218:221], v[8:11]
	v_mfma_f32_16x16x32_bf16 v[4:7], v[174:177], v[214:217], v[4:7]
	v_mfma_f32_16x16x32_bf16 v[4:7], v[186:189], v[218:221], v[4:7]
	s_barrier
	s_add_u32 s100, s30, 0x100000
	s_addc_u32 s101, s31, 0
	s_mov_b32 m0, s16
	ds_read_b128 v[144:147], v252 offset:32768
	ds_read_b128 v[154:157], v252 offset:33792
	global_load_lds_dwordx4 v138, s[100:101]
	s_mov_b32 m0, s17
	ds_read_b128 v[158:161], v252 offset:34816
	ds_read_b128 v[162:165], v252 offset:35840
	global_load_lds_dwordx4 v134, s[100:101]
	ds_read_b128 v[166:169], v252 offset:49152
	ds_read_b128 v[170:173], v252 offset:50176
	ds_read_b128 v[174:177], v252 offset:51200
	ds_read_b128 v[186:189], v252 offset:52224
	ds_read_b128 v[190:193], v153 offset:32768
	ds_read_b128 v[194:197], v153 offset:33792
	ds_read_b128 v[198:201], v153 offset:34816
	ds_read_b128 v[202:205], v153 offset:35840
	ds_read_b128 v[206:209], v153 offset:36864
	ds_read_b128 v[210:213], v153 offset:37888
	ds_read_b128 v[214:217], v153 offset:38912
	ds_read_b128 v[218:221], v153 offset:39936
	s_waitcnt vmcnt(9)
	s_waitcnt lgkmcnt(0)
	s_barrier
	v_mfma_f32_16x16x32_bf16 v[128:131], v[144:147], v[190:193], v[128:131]
	v_mfma_f32_16x16x32_bf16 v[128:131], v[154:157], v[194:197], v[128:131]
	v_mfma_f32_16x16x32_bf16 v[124:127], v[158:161], v[190:193], v[124:127]
	v_mfma_f32_16x16x32_bf16 v[124:127], v[162:165], v[194:197], v[124:127]
	v_mfma_f32_16x16x32_bf16 v[112:115], v[144:147], v[198:201], v[112:115]
	v_mfma_f32_16x16x32_bf16 v[112:115], v[154:157], v[202:205], v[112:115]
	v_mfma_f32_16x16x32_bf16 v[108:111], v[158:161], v[198:201], v[108:111]
	v_mfma_f32_16x16x32_bf16 v[108:111], v[162:165], v[202:205], v[108:111]
	v_mfma_f32_16x16x32_bf16 v[96:99], v[144:147], v[206:209], v[96:99]
	v_mfma_f32_16x16x32_bf16 v[96:99], v[154:157], v[210:213], v[96:99]
	v_mfma_f32_16x16x32_bf16 v[92:95], v[158:161], v[206:209], v[92:95]
	v_mfma_f32_16x16x32_bf16 v[92:95], v[162:165], v[210:213], v[92:95]
	v_mfma_f32_16x16x32_bf16 v[80:83], v[144:147], v[214:217], v[80:83]
	v_mfma_f32_16x16x32_bf16 v[80:83], v[154:157], v[218:221], v[80:83]
	v_mfma_f32_16x16x32_bf16 v[76:79], v[158:161], v[214:217], v[76:79]
	v_mfma_f32_16x16x32_bf16 v[76:79], v[162:165], v[218:221], v[76:79]
	v_mfma_f32_16x16x32_bf16 v[120:123], v[166:169], v[190:193], v[120:123]
	v_mfma_f32_16x16x32_bf16 v[120:123], v[170:173], v[194:197], v[120:123]
	v_mfma_f32_16x16x32_bf16 v[116:119], v[174:177], v[190:193], v[116:119]
	v_mfma_f32_16x16x32_bf16 v[116:119], v[186:189], v[194:197], v[116:119]
	v_mfma_f32_16x16x32_bf16 v[104:107], v[166:169], v[198:201], v[104:107]
	v_mfma_f32_16x16x32_bf16 v[104:107], v[170:173], v[202:205], v[104:107]
	v_mfma_f32_16x16x32_bf16 v[100:103], v[174:177], v[198:201], v[100:103]
	v_mfma_f32_16x16x32_bf16 v[100:103], v[186:189], v[202:205], v[100:103]
	v_mfma_f32_16x16x32_bf16 v[88:91], v[166:169], v[206:209], v[88:91]
	v_mfma_f32_16x16x32_bf16 v[88:91], v[170:173], v[210:213], v[88:91]
	v_mfma_f32_16x16x32_bf16 v[84:87], v[174:177], v[206:209], v[84:87]
	v_mfma_f32_16x16x32_bf16 v[84:87], v[186:189], v[210:213], v[84:87]
	v_mfma_f32_16x16x32_bf16 v[72:75], v[166:169], v[214:217], v[72:75]
	v_mfma_f32_16x16x32_bf16 v[72:75], v[170:173], v[218:221], v[72:75]
	v_mfma_f32_16x16x32_bf16 v[68:71], v[174:177], v[214:217], v[68:71]
	v_mfma_f32_16x16x32_bf16 v[68:71], v[186:189], v[218:221], v[68:71]
	s_barrier
	s_add_u32 s28, s28, 0x80
	s_addc_u32 s29, s29, 0
	s_add_i32 m0, s38, 0x18000
	ds_read_b128 v[190:193], v153 offset:49152
	ds_read_b128 v[194:197], v153 offset:50176
	global_load_lds_dwordx4 v136, s[28:29]
	s_add_i32 m0, s38, 0x1a000
	s_add_u32 s98, s98, 0x80
	s_addc_u32 s99, s99, 0
	ds_read_b128 v[198:201], v153 offset:51200
	global_load_lds_dwordx4 v132, s[28:29]
	s_add_i32 m0, s38, 0x1c000
	ds_read_b128 v[202:205], v153 offset:52224
	ds_read_b128 v[206:209], v153 offset:53248
	global_load_lds_dwordx4 v136, s[98:99]
	s_add_i32 m0, s38, 0x1e000
	s_add_u32 s30, s30, 0x80
	s_addc_u32 s31, s31, 0
	ds_read_b128 v[210:213], v153 offset:54272
	ds_read_b128 v[214:217], v153 offset:55296
	global_load_lds_dwordx4 v132, s[98:99]
	s_mov_b32 m0, s45
	ds_read_b128 v[218:221], v153 offset:56320
	global_load_lds_dwordx4 v138, s[30:31]
	s_mov_b32 m0, s46
	s_nop 0
	global_load_lds_dwordx4 v134, s[30:31]
	s_waitcnt vmcnt(9)
	s_waitcnt lgkmcnt(0)
	s_barrier
	v_mfma_f32_16x16x32_bf16 v[64:67], v[144:147], v[190:193], v[64:67]
	v_mfma_f32_16x16x32_bf16 v[64:67], v[154:157], v[194:197], v[64:67]
	v_mfma_f32_16x16x32_bf16 v[60:63], v[158:161], v[190:193], v[60:63]
	v_mfma_f32_16x16x32_bf16 v[60:63], v[162:165], v[194:197], v[60:63]
	v_mfma_f32_16x16x32_bf16 v[48:51], v[144:147], v[198:201], v[48:51]
	v_mfma_f32_16x16x32_bf16 v[48:51], v[154:157], v[202:205], v[48:51]
	v_mfma_f32_16x16x32_bf16 v[44:47], v[158:161], v[198:201], v[44:47]
	v_mfma_f32_16x16x32_bf16 v[44:47], v[162:165], v[202:205], v[44:47]
	v_mfma_f32_16x16x32_bf16 v[32:35], v[144:147], v[206:209], v[32:35]
	v_mfma_f32_16x16x32_bf16 v[32:35], v[154:157], v[210:213], v[32:35]
	v_mfma_f32_16x16x32_bf16 v[28:31], v[158:161], v[206:209], v[28:31]
	v_mfma_f32_16x16x32_bf16 v[28:31], v[162:165], v[210:213], v[28:31]
	v_mfma_f32_16x16x32_bf16 v[16:19], v[144:147], v[214:217], v[16:19]
	v_mfma_f32_16x16x32_bf16 v[16:19], v[154:157], v[218:221], v[16:19]
	v_mfma_f32_16x16x32_bf16 v[12:15], v[158:161], v[214:217], v[12:15]
	v_mfma_f32_16x16x32_bf16 v[12:15], v[162:165], v[218:221], v[12:15]
	v_mfma_f32_16x16x32_bf16 v[56:59], v[166:169], v[190:193], v[56:59]
	v_mfma_f32_16x16x32_bf16 v[56:59], v[170:173], v[194:197], v[56:59]
	v_mfma_f32_16x16x32_bf16 v[52:55], v[174:177], v[190:193], v[52:55]
	v_mfma_f32_16x16x32_bf16 v[52:55], v[186:189], v[194:197], v[52:55]
	v_mfma_f32_16x16x32_bf16 v[40:43], v[166:169], v[198:201], v[40:43]
	v_mfma_f32_16x16x32_bf16 v[40:43], v[170:173], v[202:205], v[40:43]
	v_mfma_f32_16x16x32_bf16 v[36:39], v[174:177], v[198:201], v[36:39]
	v_mfma_f32_16x16x32_bf16 v[36:39], v[186:189], v[202:205], v[36:39]
	v_mfma_f32_16x16x32_bf16 v[24:27], v[166:169], v[206:209], v[24:27]
	v_mfma_f32_16x16x32_bf16 v[24:27], v[170:173], v[210:213], v[24:27]
	v_mfma_f32_16x16x32_bf16 v[20:23], v[174:177], v[206:209], v[20:23]
	v_mfma_f32_16x16x32_bf16 v[20:23], v[186:189], v[210:213], v[20:23]
	v_mfma_f32_16x16x32_bf16 v[8:11], v[166:169], v[214:217], v[8:11]
	v_mfma_f32_16x16x32_bf16 v[8:11], v[170:173], v[218:221], v[8:11]
	v_mfma_f32_16x16x32_bf16 v[4:7], v[174:177], v[214:217], v[4:7]
	v_mfma_f32_16x16x32_bf16 v[4:7], v[186:189], v[218:221], v[4:7]
	s_barrier
	s_add_i32 s20, s20, 2
	s_add_u32 s10, s10, 0x100
	s_addc_u32 s11, s11, 0
	s_add_u32 s0, s0, 0x100
	s_addc_u32 s1, s1, 0
	s_cmp_gt_u32 s20, 61
	s_cbranch_scc0 .LBB0_1226
	s_and_b64 vcc, exec, s[48:49]
	s_cbranch_vccz .LBB0_1229
	s_barrier
